# plus: non-temporal hint on the read-once f32 weight loads of the layer-1 weight conversion
# baseline (speedup 1.0000x reference)
; __device__ __forceinline__ void conv_weight(const float* W, int ldw, int K, int Nphys, int Nvalid, int mode, const float* g, bf16_t* WT, LAS float* scr, int gw, int NGW, int lane, int& rot) {
;     ...
; #pragma unroll
;         for (int i = 0; i < 32; ++i) { const int kk = 2 * i + (lane >> 5); wv_[i] = ok ? W[(size_t)(k0 + kk) * ldw + col] : 0.f; }
; #pragma unroll
;         for (int i = 0; i < 32; ++i) { const int kk = 2 * i + (lane >> 5); float v = wv_[i]; if (g) v *= g[k0 + kk]; scr[kk * 33 + (lane & 31)] = v; }
.LBB0_1612:
	s_or_b64 exec, exec, s[10:11]
	v_ashrrev_i32_e32 v5, 31, v4
	v_lshl_add_u64 v[4:5], v[4:5], 2, s[6:7]
	global_load_dword v4, v[4:5], off nt
	v_add_u32_e32 v7, 0x400, v43
	s_ashr_i32 s9, s8, 31
	s_add_i32 s0, s0, s22
	s_add_i32 s3, s3, s12
	v_add_u32_e32 v8, s2, v8
	s_cmpk_lt_i32 s0, 0xb00
	s_waitcnt vmcnt(0)
	v_mul_f32_e32 v6, v76, v4
	v_or_b32_e32 v4, s8, v12
	v_ashrrev_i32_e32 v5, 31, v4
	v_lshl_add_u64 v[4:5], v[4:5], 2, s[6:7]
	global_load_dword v4, v[4:5], off nt
	s_waitcnt vmcnt(0)
	v_mul_f32_e32 v4, v72, v4
	ds_write2_b32 v43, v6, v4 offset1:66
	v_or_b32_e32 v4, s8, v0
	v_ashrrev_i32_e32 v5, 31, v4
	v_lshl_add_u64 v[4:5], v[4:5], 2, s[6:7]
	global_load_dword v4, v[4:5], off nt
	s_waitcnt vmcnt(0)
	v_mul_f32_e32 v6, v75, v4
	v_or_b32_e32 v4, s8, v14
	v_ashrrev_i32_e32 v5, 31, v4
	v_lshl_add_u64 v[4:5], v[4:5], 2, s[6:7]
	global_load_dword v4, v[4:5], off nt
	s_waitcnt vmcnt(0)
	v_mul_f32_e32 v4, v71, v4
	ds_write2_b32 v43, v6, v4 offset0:132 offset1:198
	v_or_b32_e32 v4, s8, v15
	v_ashrrev_i32_e32 v5, 31, v4
	v_lshl_add_u64 v[4:5], v[4:5], 2, s[6:7]
	global_load_dword v4, v[4:5], off nt
	s_waitcnt vmcnt(0)
	v_mul_f32_e32 v6, v74, v4
	v_or_b32_e32 v4, s8, v16
	v_ashrrev_i32_e32 v5, 31, v4
	v_lshl_add_u64 v[4:5], v[4:5], 2, s[6:7]
	global_load_dword v4, v[4:5], off nt
	s_waitcnt vmcnt(0)
	v_mul_f32_e32 v4, v70, v4
	ds_write2_b32 v7, v6, v4 offset0:8 offset1:74
	v_or_b32_e32 v4, s8, v17
	v_ashrrev_i32_e32 v5, 31, v4
	v_lshl_add_u64 v[4:5], v[4:5], 2, s[6:7]
	global_load_dword v4, v[4:5], off nt
	s_waitcnt vmcnt(0)
	v_mul_f32_e32 v6, v73, v4
	v_or_b32_e32 v4, s8, v18
	v_ashrrev_i32_e32 v5, 31, v4
	v_lshl_add_u64 v[4:5], v[4:5], 2, s[6:7]
	global_load_dword v4, v[4:5], off nt
	s_waitcnt vmcnt(0)
	v_mul_f32_e32 v4, v64, v4
	ds_write2_b32 v7, v6, v4 offset0:140 offset1:206
	v_or_b32_e32 v4, s8, v19
	v_ashrrev_i32_e32 v5, 31, v4
	v_lshl_add_u64 v[4:5], v[4:5], 2, s[6:7]
	global_load_dword v4, v[4:5], off nt
	v_add_u32_e32 v7, 0x800, v43
	v_add_u32_e32 v64, s13, v10
	v_add_u32_e32 v10, s2, v10
	s_waitcnt vmcnt(0)
	v_mul_f32_e32 v6, v69, v4
	v_or_b32_e32 v4, s8, v20
	v_ashrrev_i32_e32 v5, 31, v4
	v_lshl_add_u64 v[4:5], v[4:5], 2, s[6:7]
	global_load_dword v4, v[4:5], off nt
	s_waitcnt vmcnt(0)
	v_mul_f32_e32 v4, v66, v4
	ds_write2_b32 v7, v6, v4 offset0:16 offset1:82
	v_or_b32_e32 v4, s8, v21
	v_ashrrev_i32_e32 v5, 31, v4
	v_lshl_add_u64 v[4:5], v[4:5], 2, s[6:7]
	global_load_dword v4, v[4:5], off nt
	s_waitcnt vmcnt(0)
	v_mul_f32_e32 v6, v68, v4
	v_or_b32_e32 v4, s8, v22
	v_ashrrev_i32_e32 v5, 31, v4
	v_lshl_add_u64 v[4:5], v[4:5], 2, s[6:7]
	global_load_dword v4, v[4:5], off nt
	s_waitcnt vmcnt(0)
	v_mul_f32_e32 v4, v63, v4
	ds_write2_b32 v7, v6, v4 offset0:148 offset1:214
	v_or_b32_e32 v4, s8, v23
	v_ashrrev_i32_e32 v5, 31, v4
	v_lshl_add_u64 v[4:5], v[4:5], 2, s[6:7]
	global_load_dword v4, v[4:5], off nt
	v_add_u32_e32 v7, 0xc00, v43
	s_waitcnt vmcnt(0)
	v_mul_f32_e32 v6, v67, v4
	v_or_b32_e32 v4, s8, v24
	v_ashrrev_i32_e32 v5, 31, v4
	v_lshl_add_u64 v[4:5], v[4:5], 2, s[6:7]
	global_load_dword v4, v[4:5], off nt
	s_waitcnt vmcnt(0)
	v_mul_f32_e32 v4, v62, v4
	ds_write2_b32 v7, v6, v4 offset0:24 offset1:90
	v_or_b32_e32 v4, s8, v25
	v_ashrrev_i32_e32 v5, 31, v4
	v_lshl_add_u64 v[4:5], v[4:5], 2, s[6:7]
	global_load_dword v4, v[4:5], off nt
	s_waitcnt vmcnt(0)
	v_mul_f32_e32 v6, v65, v4
	v_or_b32_e32 v4, s8, v26
	v_ashrrev_i32_e32 v5, 31, v4
	v_lshl_add_u64 v[4:5], v[4:5], 2, s[6:7]
	global_load_dword v4, v[4:5], off nt
	v_ashrrev_i32_e32 v65, 31, v64
	v_lshlrev_b64 v[66:67], 11, v[64:65]
	s_waitcnt vmcnt(0)
	v_mul_f32_e32 v4, v56, v4
	ds_write2_b32 v7, v6, v4 offset0:156 offset1:222
	v_or_b32_e32 v4, s8, v27
	v_ashrrev_i32_e32 v5, 31, v4
	v_lshl_add_u64 v[4:5], v[4:5], 2, s[6:7]
	global_load_dword v4, v[4:5], off nt
	v_add_u32_e32 v7, 0x1000, v43
	s_waitcnt vmcnt(0)
	v_mul_f32_e32 v6, v61, v4
	v_or_b32_e32 v4, s8, v28
	v_ashrrev_i32_e32 v5, 31, v4
	v_lshl_add_u64 v[4:5], v[4:5], 2, s[6:7]
	global_load_dword v4, v[4:5], off nt
	s_waitcnt vmcnt(0)
	v_mul_f32_e32 v4, v58, v4
	ds_write2_b32 v7, v6, v4 offset0:32 offset1:98
	v_or_b32_e32 v4, s8, v29
	v_ashrrev_i32_e32 v5, 31, v4
	v_lshl_add_u64 v[4:5], v[4:5], 2, s[6:7]
	global_load_dword v4, v[4:5], off nt
	s_waitcnt vmcnt(0)
	v_mul_f32_e32 v6, v60, v4
	v_or_b32_e32 v4, s8, v30
	v_ashrrev_i32_e32 v5, 31, v4
	v_lshl_add_u64 v[4:5], v[4:5], 2, s[6:7]
	global_load_dword v4, v[4:5], off nt
	s_waitcnt vmcnt(0)
	v_mul_f32_e32 v4, v55, v4
	ds_write2_b32 v7, v6, v4 offset0:164 offset1:230
	v_or_b32_e32 v4, s8, v31
	v_ashrrev_i32_e32 v5, 31, v4
	v_lshl_add_u64 v[4:5], v[4:5], 2, s[6:7]
	global_load_dword v4, v[4:5], off nt
	v_add_u32_e32 v7, 0x1400, v43
	s_waitcnt vmcnt(0)
	v_mul_f32_e32 v6, v59, v4
	v_or_b32_e32 v4, s8, v32
	v_ashrrev_i32_e32 v5, 31, v4
	v_lshl_add_u64 v[4:5], v[4:5], 2, s[6:7]
	global_load_dword v4, v[4:5], off nt
	s_waitcnt vmcnt(0)
	v_mul_f32_e32 v4, v54, v4
	ds_write2_b32 v7, v6, v4 offset0:40 offset1:106
	v_or_b32_e32 v4, s8, v33
	v_ashrrev_i32_e32 v5, 31, v4
	v_lshl_add_u64 v[4:5], v[4:5], 2, s[6:7]
	global_load_dword v4, v[4:5], off nt
	s_waitcnt vmcnt(0)
	v_mul_f32_e32 v6, v57, v4
	v_or_b32_e32 v4, s8, v34
	v_ashrrev_i32_e32 v5, 31, v4
	v_lshl_add_u64 v[4:5], v[4:5], 2, s[6:7]
	global_load_dword v4, v[4:5], off nt
	s_waitcnt vmcnt(0)
	v_mul_f32_e32 v4, v49, v4
	ds_write2_b32 v7, v6, v4 offset0:172 offset1:238
	v_or_b32_e32 v4, s8, v35
	v_ashrrev_i32_e32 v5, 31, v4
	v_lshl_add_u64 v[4:5], v[4:5], 2, s[6:7]
	global_load_dword v4, v[4:5], off nt
	v_add_u32_e32 v7, 0x1800, v43
	s_waitcnt vmcnt(0)
; #define LAS __attribute__((address_space(3)))
; __device__ __forceinline__ unsigned pk2(float lo, float hi) { return f2bf(lo) | (f2bf(hi) << 16); }
; __device__ __forceinline__ void conv_weight(const float* W, int ldw, int K, int Nphys, int Nvalid, int mode, const float* g, bf16_t* WT, LAS float* scr, int gw, int NGW, int lane, int& rot) {
;     ...
;         for (int i = 0; i < 32; ++i) { const int kk = 2 * i + (lane >> 5); float v = wv_[i]; if (g) v *= g[k0 + kk]; scr[kk * 33 + (lane & 31)] = v; }
;         asm volatile("s_waitcnt lgkmcnt(0)" ::: "memory");
;         const int c = lane & 7;
; #pragma unroll
;         for (int j = 0; j < 4; ++j) { const int n = (lane >> 3) + 8 * j; const LAS float* s = scr + (8 * c) * 33 + n;
;             u32x4 o; o.x = pk2(s[0 * 33], s[1 * 33]); o.y = pk2(s[2 * 33], s[3 * 33]); o.z = pk2(s[4 * 33], s[5 * 33]); o.w = pk2(s[6 * 33], s[7 * 33]);
;             *(u32x4*)(WT + (size_t)(n0 + n) * K + k0 + 8 * c) = o; }
;         asm volatile("s_waitcnt lgkmcnt(0)" ::: "memory");
	v_mul_f32_e32 v6, v53, v4
	v_or_b32_e32 v4, s8, v36
	v_ashrrev_i32_e32 v5, 31, v4
	v_lshl_add_u64 v[4:5], v[4:5], 2, s[6:7]
	global_load_dword v4, v[4:5], off nt
	s_waitcnt vmcnt(0)
	v_mul_f32_e32 v4, v50, v4
	ds_write2_b32 v7, v6, v4 offset0:48 offset1:114
	v_or_b32_e32 v4, s8, v37
	v_ashrrev_i32_e32 v5, 31, v4
	v_lshl_add_u64 v[4:5], v[4:5], 2, s[6:7]
	global_load_dword v4, v[4:5], off nt
	s_waitcnt vmcnt(0)
	v_mul_f32_e32 v6, v52, v4
	v_or_b32_e32 v4, s8, v38
	v_ashrrev_i32_e32 v5, 31, v4
	v_lshl_add_u64 v[4:5], v[4:5], 2, s[6:7]
	global_load_dword v4, v[4:5], off nt
	s_waitcnt vmcnt(0)
	v_mul_f32_e32 v4, v48, v4
	ds_write2_b32 v7, v6, v4 offset0:180 offset1:246
	v_or_b32_e32 v4, s8, v39
	v_ashrrev_i32_e32 v5, 31, v4
	v_lshl_add_u64 v[4:5], v[4:5], 2, s[6:7]
	global_load_dword v4, v[4:5], off nt
	v_add_u32_e32 v7, 0x1c00, v43
	s_waitcnt vmcnt(0)
	v_mul_f32_e32 v6, v51, v4
	v_or_b32_e32 v4, s8, v40
	v_ashrrev_i32_e32 v5, 31, v4
	v_lshl_add_u64 v[4:5], v[4:5], 2, s[6:7]
	global_load_dword v4, v[4:5], off nt
	s_waitcnt vmcnt(0)
	v_mul_f32_e32 v4, v45, v4
	ds_write2_b32 v7, v6, v4 offset0:56 offset1:122
	v_or_b32_e32 v4, s8, v41
	v_ashrrev_i32_e32 v5, 31, v4
	v_lshl_add_u64 v[4:5], v[4:5], 2, s[6:7]
	global_load_dword v4, v[4:5], off nt
	s_waitcnt vmcnt(0)
	v_mul_f32_e32 v6, v47, v4
	v_or_b32_e32 v4, s8, v42
	v_ashrrev_i32_e32 v5, 31, v4
	v_lshl_add_u64 v[4:5], v[4:5], 2, s[6:7]
	global_load_dword v4, v[4:5], off nt
	s_waitcnt vmcnt(0)
	v_mul_f32_e32 v4, v44, v4
	ds_write2_b32 v7, v6, v4 offset0:188 offset1:254
	s_waitcnt lgkmcnt(0)
	ds_read2_b32 v[6:7], v13 offset0:33 offset1:41
	ds_read2_b32 v[44:45], v13 offset1:8
	ds_read2_b32 v[52:53], v13 offset0:66 offset1:74
	ds_read2_b32 v[54:55], v13 offset0:99 offset1:107
	v_lshl_add_u64 v[4:5], s[8:9], 1, v[2:3]
	s_mov_b32 s8, 0xffff0000
	ds_read2_b32 v[56:57], v13 offset0:132 offset1:140
	ds_read2_b32 v[58:59], v13 offset0:165 offset1:173
	s_waitcnt lgkmcnt(4)
	v_bfe_u32 v47, v44, 16, 1
	v_add3_u32 v44, v44, v47, s33
	v_bfe_u32 v47, v6, 16, 1
	v_lshrrev_b32_e32 v44, 16, v44
	v_add3_u32 v6, v6, v47, s33
	v_and_or_b32 v48, v6, s8, v44
	s_waitcnt lgkmcnt(3)
	v_bfe_u32 v6, v52, 16, 1
	v_add3_u32 v6, v52, v6, s33
	s_waitcnt lgkmcnt(2)
	v_bfe_u32 v44, v54, 16, 1
	v_lshrrev_b32_e32 v6, 16, v6
	v_add3_u32 v44, v54, v44, s33
	ds_read2_b32 v[60:61], v13 offset0:198 offset1:206
	ds_read2_b32 v[62:63], v13 offset0:231 offset1:239
	v_and_or_b32 v49, v44, s8, v6
	s_waitcnt lgkmcnt(3)
	v_bfe_u32 v6, v56, 16, 1
	v_add3_u32 v6, v56, v6, s33
	s_waitcnt lgkmcnt(2)
	v_bfe_u32 v44, v58, 16, 1
	v_lshrrev_b32_e32 v6, 16, v6
	v_add3_u32 v44, v58, v44, s33
	v_and_or_b32 v50, v44, s8, v6
	s_waitcnt lgkmcnt(1)
	v_bfe_u32 v6, v60, 16, 1
	v_add3_u32 v6, v60, v6, s33
	s_waitcnt lgkmcnt(0)
	v_bfe_u32 v44, v62, 16, 1
	v_lshrrev_b32_e32 v6, 16, v6
	v_add3_u32 v44, v62, v44, s33
	v_and_or_b32 v51, v44, s8, v6
	v_bfe_u32 v6, v45, 16, 1
	v_add3_u32 v6, v45, v6, s33
	v_bfe_u32 v44, v7, 16, 1
	v_lshl_add_u64 v[66:67], v[4:5], 0, v[66:67]
	v_lshrrev_b32_e32 v6, 16, v6
	v_add3_u32 v7, v7, v44, s33
	global_store_dwordx4 v[66:67], v[48:51], off
	v_add_u32_e32 v66, 16, v64
	v_ashrrev_i32_e32 v67, 31, v66
	v_and_or_b32 v48, v7, s8, v6
	v_bfe_u32 v6, v53, 16, 1
	v_add3_u32 v6, v53, v6, s33
	v_bfe_u32 v7, v55, 16, 1
	v_lshrrev_b32_e32 v6, 16, v6
	v_add3_u32 v7, v55, v7, s33
	v_and_or_b32 v49, v7, s8, v6
	v_bfe_u32 v6, v57, 16, 1
	v_add3_u32 v6, v57, v6, s33
	v_bfe_u32 v7, v59, 16, 1
	v_lshrrev_b32_e32 v6, 16, v6
	v_add3_u32 v7, v59, v7, s33
	v_and_or_b32 v50, v7, s8, v6
	v_bfe_u32 v6, v61, 16, 1
	v_add3_u32 v6, v61, v6, s33
	v_bfe_u32 v7, v63, 16, 1
	v_lshrrev_b32_e32 v6, 16, v6
	v_add3_u32 v7, v63, v7, s33
	v_and_or_b32 v51, v7, s8, v6
	v_add_u32_e32 v6, 8, v64
	v_ashrrev_i32_e32 v7, 31, v6
	v_lshlrev_b64 v[6:7], 11, v[6:7]
	v_lshl_add_u64 v[6:7], v[4:5], 0, v[6:7]
	global_store_dwordx4 v[6:7], v[48:51], off
	ds_read2_b32 v[6:7], v13 offset0:49 offset1:57
	ds_read2_b32 v[44:45], v13 offset0:16 offset1:24
	ds_read2_b32 v[52:53], v13 offset0:82 offset1:90
	ds_read2_b32 v[54:55], v13 offset0:115 offset1:123
	ds_read2_b32 v[56:57], v13 offset0:148 offset1:156
	ds_read2_b32 v[58:59], v13 offset0:181 offset1:189
	ds_read2_b32 v[60:61], v13 offset0:214 offset1:222
	ds_read2_b32 v[62:63], v13 offset0:247 offset1:255
	v_lshlrev_b64 v[66:67], 11, v[66:67]
	s_waitcnt lgkmcnt(6)
	v_bfe_u32 v47, v44, 16, 1
	v_add3_u32 v44, v44, v47, s33
	v_bfe_u32 v47, v6, 16, 1
	v_lshrrev_b32_e32 v44, 16, v44
	v_add3_u32 v6, v6, v47, s33
	v_and_or_b32 v48, v6, s8, v44
	s_waitcnt lgkmcnt(5)
	v_bfe_u32 v6, v52, 16, 1
	v_add3_u32 v6, v52, v6, s33
	s_waitcnt lgkmcnt(4)
	v_bfe_u32 v44, v54, 16, 1
	v_lshrrev_b32_e32 v6, 16, v6
	v_add3_u32 v44, v54, v44, s33
	v_and_or_b32 v49, v44, s8, v6
	s_waitcnt lgkmcnt(3)
	v_bfe_u32 v6, v56, 16, 1
	v_add3_u32 v6, v56, v6, s33
	s_waitcnt lgkmcnt(2)
	v_bfe_u32 v44, v58, 16, 1
	v_lshrrev_b32_e32 v6, 16, v6
	v_add3_u32 v44, v58, v44, s33
	v_and_or_b32 v50, v44, s8, v6
	s_waitcnt lgkmcnt(1)
	v_bfe_u32 v6, v60, 16, 1
	v_add3_u32 v6, v60, v6, s33
	s_waitcnt lgkmcnt(0)
	v_bfe_u32 v44, v62, 16, 1
	v_lshrrev_b32_e32 v6, 16, v6
	v_add3_u32 v44, v62, v44, s33
	v_and_or_b32 v51, v44, s8, v6
	v_bfe_u32 v6, v45, 16, 1
	v_add3_u32 v6, v45, v6, s33
	v_bfe_u32 v44, v7, 16, 1
	v_lshl_add_u64 v[66:67], v[4:5], 0, v[66:67]
	v_lshrrev_b32_e32 v6, 16, v6
	v_add3_u32 v7, v7, v44, s33
	global_store_dwordx4 v[66:67], v[48:51], off
	s_nop 1
	v_and_or_b32 v48, v7, s8, v6
	v_bfe_u32 v6, v53, 16, 1
	v_add3_u32 v6, v53, v6, s33
	v_bfe_u32 v7, v55, 16, 1
	v_lshrrev_b32_e32 v6, 16, v6
	v_add3_u32 v7, v55, v7, s33
	v_and_or_b32 v49, v7, s8, v6
	v_bfe_u32 v6, v57, 16, 1
	v_add3_u32 v6, v57, v6, s33
	v_bfe_u32 v7, v59, 16, 1
	v_lshrrev_b32_e32 v6, 16, v6
	v_add3_u32 v7, v59, v7, s33
	v_and_or_b32 v50, v7, s8, v6
	v_bfe_u32 v6, v61, 16, 1
	v_add3_u32 v6, v61, v6, s33
	v_bfe_u32 v7, v63, 16, 1
	v_lshrrev_b32_e32 v6, 16, v6
	v_add3_u32 v7, v63, v7, s33
	v_and_or_b32 v51, v7, s8, v6
	v_add_u32_e32 v6, 24, v64
	v_ashrrev_i32_e32 v7, 31, v6
	v_lshlrev_b64 v[6:7], 11, v[6:7]
	v_lshl_add_u64 v[4:5], v[4:5], 0, v[6:7]
	global_store_dwordx4 v[4:5], v[48:51], off
	s_waitcnt lgkmcnt(0)
	s_cbranch_scc0 .LBB0_1679
; __device__ __forceinline__ void conv_weight(const float* W, int ldw, int K, int Nphys, int Nvalid, int mode, const float* g, bf16_t* WT, LAS float* scr, int gw, int NGW, int lane, int& rot) {
;     ...
;         const int kb = it / nblk, nb = it % nblk, k0 = 64 * kb, n0 = 32 * nb;
;         const int prow = n0 + (lane & 31); const bool ok = prow < Nvalid; const int col = ok ? colmap(mode, prow) : 0;
;         float wv_[32];
; #pragma unroll
;         for (int i = 0; i < 32; ++i) { const int kk = 2 * i + (lane >> 5); wv_[i] = ok ? W[(size_t)(k0 + kk) * ldw + col] : 0.f; }
.LBB0_1613:
	s_mul_hi_i32 s8, s0, 0x2e8ba2e9
	s_lshr_b32 s9, s8, 31
	s_ashr_i32 s10, s8, 5
	s_add_i32 s10, s10, s9
	s_mul_i32 s13, s10, 0xffffea00
	s_add_i32 s13, s13, s1
	v_add_u32_e32 v6, s13, v8
	v_cmp_gt_i32_e32 vcc, s87, v6
	v_mov_b64_e32 v[4:5], 0
	s_and_saveexec_b64 s[8:9], vcc
	s_mul_i32 s16, s10, 0xfffff500
	s_bfe_i32 s11, s0, 0x10002
	s_add_i32 s16, s3, s16
	s_and_b32 s11, s11, 0xb00
	s_and_b32 s16, s16, 0xffffff80
	s_add_i32 s11, s11, s16
	v_and_b32_e32 v4, 0x7f, v6
	v_or_b32_e32 v4, s11, v4
	v_ashrrev_i32_e32 v5, 31, v4
	s_or_b64 exec, exec, s[8:9]
	s_lshl_b32 s8, s10, 6
	v_lshl_add_u64 v[6:7], v[4:5], 2, s[4:5]
	v_or_b32_e32 v4, s8, v9
	s_waitcnt vmcnt(4)
	v_mov_b32_e32 v72, 0
	v_mov_b32_e32 v76, 0
	s_and_saveexec_b64 s[10:11], vcc
	s_cbranch_execz .LBB0_1617
	s_movk_i32 s9, 0x5800
	v_mad_i64_i32 v[44:45], s[16:17], v4, s9, v[6:7]
	global_load_dword v76, v[44:45], off nt
.LBB0_1617:
	s_or_b64 exec, exec, s[10:11]
	s_and_saveexec_b64 s[10:11], vcc
	s_cbranch_execz .LBB0_1619
	v_or_b32_e32 v5, 2, v4
	s_movk_i32 s9, 0x5800
	v_mad_i64_i32 v[44:45], s[16:17], v5, s9, v[6:7]
	global_load_dword v72, v[44:45], off nt
.LBB0_1619:
	s_or_b64 exec, exec, s[10:11]
	v_mov_b32_e32 v71, 0
	v_mov_b32_e32 v75, 0
	s_and_saveexec_b64 s[10:11], vcc
	s_cbranch_execz .LBB0_1621
	v_or_b32_e32 v5, 4, v4
	s_movk_i32 s9, 0x5800
	v_mad_i64_i32 v[44:45], s[16:17], v5, s9, v[6:7]
	global_load_dword v75, v[44:45], off nt
.LBB0_1621:
	s_or_b64 exec, exec, s[10:11]
	s_and_saveexec_b64 s[10:11], vcc
	s_cbranch_execz .LBB0_1623
	v_or_b32_e32 v5, 6, v4
	s_movk_i32 s9, 0x5800
	v_mad_i64_i32 v[44:45], s[16:17], v5, s9, v[6:7]
	global_load_dword v71, v[44:45], off nt
.LBB0_1623:
	s_or_b64 exec, exec, s[10:11]
	v_mov_b32_e32 v70, 0
	v_mov_b32_e32 v74, 0
	s_and_saveexec_b64 s[10:11], vcc
	s_cbranch_execz .LBB0_1625
	v_or_b32_e32 v5, 8, v4
	s_movk_i32 s9, 0x5800
	v_mad_i64_i32 v[44:45], s[16:17], v5, s9, v[6:7]
	global_load_dword v74, v[44:45], off nt
.LBB0_1625:
	s_or_b64 exec, exec, s[10:11]
	s_and_saveexec_b64 s[10:11], vcc
	s_cbranch_execz .LBB0_1627
	v_or_b32_e32 v5, 10, v4
	s_movk_i32 s9, 0x5800
	v_mad_i64_i32 v[44:45], s[16:17], v5, s9, v[6:7]
	global_load_dword v70, v[44:45], off nt
.LBB0_1627:
	s_or_b64 exec, exec, s[10:11]
	v_mov_b32_e32 v64, 0
	v_mov_b32_e32 v73, 0
	s_and_saveexec_b64 s[10:11], vcc
	s_cbranch_execz .LBB0_1629
	v_or_b32_e32 v5, 12, v4
	s_movk_i32 s9, 0x5800
	v_mad_i64_i32 v[44:45], s[16:17], v5, s9, v[6:7]
	global_load_dword v73, v[44:45], off nt
.LBB0_1629:
	s_or_b64 exec, exec, s[10:11]
	s_and_saveexec_b64 s[10:11], vcc
	s_cbranch_execz .LBB0_1631
	v_or_b32_e32 v5, 14, v4
	s_movk_i32 s9, 0x5800
	v_mad_i64_i32 v[44:45], s[16:17], v5, s9, v[6:7]
	global_load_dword v64, v[44:45], off nt
.LBB0_1631:
	s_or_b64 exec, exec, s[10:11]
	v_mov_b32_e32 v66, 0
	v_mov_b32_e32 v69, 0
	s_and_saveexec_b64 s[10:11], vcc
	s_cbranch_execz .LBB0_1633
	v_or_b32_e32 v5, 16, v4
	s_movk_i32 s9, 0x5800
	v_mad_i64_i32 v[44:45], s[16:17], v5, s9, v[6:7]
	global_load_dword v69, v[44:45], off nt
.LBB0_1633:
	s_or_b64 exec, exec, s[10:11]
	s_and_saveexec_b64 s[10:11], vcc
	s_cbranch_execz .LBB0_1635
	v_or_b32_e32 v5, 18, v4
	s_movk_i32 s9, 0x5800
	v_mad_i64_i32 v[44:45], s[16:17], v5, s9, v[6:7]
	global_load_dword v66, v[44:45], off nt
.LBB0_1635:
	s_or_b64 exec, exec, s[10:11]
	v_mov_b32_e32 v63, 0
	v_mov_b32_e32 v68, 0
	s_and_saveexec_b64 s[10:11], vcc
	s_cbranch_execz .LBB0_1637
	v_or_b32_e32 v5, 20, v4
	s_movk_i32 s9, 0x5800
	v_mad_i64_i32 v[44:45], s[16:17], v5, s9, v[6:7]
	global_load_dword v68, v[44:45], off nt
.LBB0_1637:
	s_or_b64 exec, exec, s[10:11]
	s_and_saveexec_b64 s[10:11], vcc
	s_cbranch_execz .LBB0_1639
	v_or_b32_e32 v5, 22, v4
	s_movk_i32 s9, 0x5800
	v_mad_i64_i32 v[44:45], s[16:17], v5, s9, v[6:7]
	global_load_dword v63, v[44:45], off nt
.LBB0_1639:
	s_or_b64 exec, exec, s[10:11]
	v_mov_b32_e32 v62, 0
	v_mov_b32_e32 v67, 0
	s_and_saveexec_b64 s[10:11], vcc
	s_cbranch_execz .LBB0_1641
	v_or_b32_e32 v5, 24, v4
	s_movk_i32 s9, 0x5800
	v_mad_i64_i32 v[44:45], s[16:17], v5, s9, v[6:7]
	global_load_dword v67, v[44:45], off nt
.LBB0_1641:
	s_or_b64 exec, exec, s[10:11]
	s_and_saveexec_b64 s[10:11], vcc
	s_cbranch_execz .LBB0_1643
	v_or_b32_e32 v5, 26, v4
	s_movk_i32 s9, 0x5800
	v_mad_i64_i32 v[44:45], s[16:17], v5, s9, v[6:7]
	global_load_dword v62, v[44:45], off nt
.LBB0_1643:
	s_or_b64 exec, exec, s[10:11]
	v_mov_b32_e32 v56, 0
	v_mov_b32_e32 v65, 0
	s_and_saveexec_b64 s[10:11], vcc
	s_cbranch_execz .LBB0_1645
	v_or_b32_e32 v5, 28, v4
	s_movk_i32 s9, 0x5800
	v_mad_i64_i32 v[44:45], s[16:17], v5, s9, v[6:7]
	global_load_dword v65, v[44:45], off nt
; __device__ __forceinline__ void conv_weight(const float* W, int ldw, int K, int Nphys, int Nvalid, int mode, const float* g, bf16_t* WT, LAS float* scr, int gw, int NGW, int lane, int& rot) {
;     ...
;         for (int i = 0; i < 32; ++i) { const int kk = 2 * i + (lane >> 5); wv_[i] = ok ? W[(size_t)(k0 + kk) * ldw + col] : 0.f; }
.LBB0_1645:
	s_or_b64 exec, exec, s[10:11]
	s_and_saveexec_b64 s[10:11], vcc
	s_cbranch_execz .LBB0_1647
	v_or_b32_e32 v5, 30, v4
	s_movk_i32 s9, 0x5800
	v_mad_i64_i32 v[44:45], s[16:17], v5, s9, v[6:7]
	global_load_dword v56, v[44:45], off nt
.LBB0_1647:
	s_or_b64 exec, exec, s[10:11]
	v_mov_b32_e32 v58, 0
	v_mov_b32_e32 v61, 0
	s_and_saveexec_b64 s[10:11], vcc
	s_cbranch_execz .LBB0_1649
	v_or_b32_e32 v5, 32, v4
	s_movk_i32 s9, 0x5800
	v_mad_i64_i32 v[44:45], s[16:17], v5, s9, v[6:7]
	global_load_dword v61, v[44:45], off nt
.LBB0_1649:
	s_or_b64 exec, exec, s[10:11]
	s_and_saveexec_b64 s[10:11], vcc
	s_cbranch_execz .LBB0_1651
	v_or_b32_e32 v5, 34, v4
	s_movk_i32 s9, 0x5800
	v_mad_i64_i32 v[44:45], s[16:17], v5, s9, v[6:7]
	global_load_dword v58, v[44:45], off nt
.LBB0_1651:
	s_or_b64 exec, exec, s[10:11]
	v_mov_b32_e32 v55, 0
	v_mov_b32_e32 v60, 0
	s_and_saveexec_b64 s[10:11], vcc
	s_cbranch_execz .LBB0_1653
	v_or_b32_e32 v5, 36, v4
	s_movk_i32 s9, 0x5800
	v_mad_i64_i32 v[44:45], s[16:17], v5, s9, v[6:7]
	global_load_dword v60, v[44:45], off nt
.LBB0_1653:
	s_or_b64 exec, exec, s[10:11]
	s_and_saveexec_b64 s[10:11], vcc
	s_cbranch_execz .LBB0_1655
	v_or_b32_e32 v5, 38, v4
	s_movk_i32 s9, 0x5800
	v_mad_i64_i32 v[44:45], s[16:17], v5, s9, v[6:7]
	global_load_dword v55, v[44:45], off nt
.LBB0_1655:
	s_or_b64 exec, exec, s[10:11]
	v_mov_b32_e32 v54, 0
	v_mov_b32_e32 v59, 0
	s_and_saveexec_b64 s[10:11], vcc
	s_cbranch_execz .LBB0_1657
	v_or_b32_e32 v5, 40, v4
	s_movk_i32 s9, 0x5800
	v_mad_i64_i32 v[44:45], s[16:17], v5, s9, v[6:7]
	global_load_dword v59, v[44:45], off nt
.LBB0_1657:
	s_or_b64 exec, exec, s[10:11]
	s_and_saveexec_b64 s[10:11], vcc
	s_cbranch_execz .LBB0_1659
	v_or_b32_e32 v5, 42, v4
	s_movk_i32 s9, 0x5800
	v_mad_i64_i32 v[44:45], s[16:17], v5, s9, v[6:7]
	global_load_dword v54, v[44:45], off nt
.LBB0_1659:
	s_or_b64 exec, exec, s[10:11]
	v_mov_b32_e32 v49, 0
	v_mov_b32_e32 v57, 0
	s_and_saveexec_b64 s[10:11], vcc
	s_cbranch_execz .LBB0_1661
	v_or_b32_e32 v5, 44, v4
	s_movk_i32 s9, 0x5800
	v_mad_i64_i32 v[44:45], s[16:17], v5, s9, v[6:7]
	global_load_dword v57, v[44:45], off nt
.LBB0_1661:
	s_or_b64 exec, exec, s[10:11]
	s_and_saveexec_b64 s[10:11], vcc
	s_cbranch_execz .LBB0_1663
	v_or_b32_e32 v5, 46, v4
	s_movk_i32 s9, 0x5800
	v_mad_i64_i32 v[44:45], s[16:17], v5, s9, v[6:7]
	global_load_dword v49, v[44:45], off nt
.LBB0_1663:
	s_or_b64 exec, exec, s[10:11]
	v_mov_b32_e32 v50, 0
	v_mov_b32_e32 v53, 0
	s_and_saveexec_b64 s[10:11], vcc
	s_cbranch_execz .LBB0_1665
	v_or_b32_e32 v5, 48, v4
	s_movk_i32 s9, 0x5800
	v_mad_i64_i32 v[44:45], s[16:17], v5, s9, v[6:7]
	global_load_dword v53, v[44:45], off nt
.LBB0_1665:
	s_or_b64 exec, exec, s[10:11]
	s_and_saveexec_b64 s[10:11], vcc
	s_cbranch_execz .LBB0_1667
	v_or_b32_e32 v5, 50, v4
	s_movk_i32 s9, 0x5800
	v_mad_i64_i32 v[44:45], s[16:17], v5, s9, v[6:7]
	global_load_dword v50, v[44:45], off nt
.LBB0_1667:
	s_or_b64 exec, exec, s[10:11]
	v_mov_b32_e32 v48, 0
	v_mov_b32_e32 v52, 0
	s_and_saveexec_b64 s[10:11], vcc
	s_cbranch_execz .LBB0_1669
	v_or_b32_e32 v5, 52, v4
	s_movk_i32 s9, 0x5800
	v_mad_i64_i32 v[44:45], s[16:17], v5, s9, v[6:7]
	global_load_dword v52, v[44:45], off nt
.LBB0_1669:
	s_or_b64 exec, exec, s[10:11]
	s_and_saveexec_b64 s[10:11], vcc
	s_cbranch_execz .LBB0_1671
	v_or_b32_e32 v5, 54, v4
	s_movk_i32 s9, 0x5800
	v_mad_i64_i32 v[44:45], s[16:17], v5, s9, v[6:7]
	global_load_dword v48, v[44:45], off nt
.LBB0_1671:
	s_or_b64 exec, exec, s[10:11]
	v_mov_b32_e32 v45, 0
	v_mov_b32_e32 v51, 0
	s_and_saveexec_b64 s[10:11], vcc
	s_cbranch_execz .LBB0_1673
	v_or_b32_e32 v5, 56, v4
	s_movk_i32 s9, 0x5800
	v_mad_i64_i32 v[78:79], s[16:17], v5, s9, v[6:7]
	global_load_dword v51, v[78:79], off nt
.LBB0_1673:
	s_or_b64 exec, exec, s[10:11]
	s_and_saveexec_b64 s[10:11], vcc
	s_cbranch_execz .LBB0_1675
	v_or_b32_e32 v5, 58, v4
	s_movk_i32 s9, 0x5800
	v_mad_i64_i32 v[44:45], s[16:17], v5, s9, v[6:7]
	global_load_dword v45, v[44:45], off nt
.LBB0_1675:
	s_or_b64 exec, exec, s[10:11]
	v_mov_b32_e32 v44, 0
	v_mov_b32_e32 v47, 0
	s_and_saveexec_b64 s[10:11], vcc
	s_cbranch_execz .LBB0_1677
	v_or_b32_e32 v5, 60, v4
	s_movk_i32 s9, 0x5800
	v_mad_i64_i32 v[78:79], s[16:17], v5, s9, v[6:7]
	global_load_dword v47, v[78:79], off nt
.LBB0_1677:
	s_or_b64 exec, exec, s[10:11]
	s_and_saveexec_b64 s[10:11], vcc
	s_cbranch_execz .LBB0_1612
	v_or_b32_e32 v5, 62, v4
	s_movk_i32 s9, 0x5800
	v_mad_i64_i32 v[6:7], s[16:17], v5, s9, v[6:7]
	global_load_dword v44, v[6:7], off nt
	s_branch .LBB0_1612

; __device__ __forceinline__ void conv_weight(const float* W, int ldw, int K, int Nphys, int Nvalid, int mode, const float* g, bf16_t* WT, LAS float* scr, int gw, int NGW, int lane, int& rot) {
;     ...
;         const int kb = it / nblk, nb = it % nblk, k0 = 64 * kb, n0 = 32 * nb;
;         const int prow = n0 + (lane & 31); const bool ok = prow < Nvalid; const int col = ok ? colmap(mode, prow) : 0;
;         float wv_[32];
; #pragma unroll
;         for (int i = 0; i < 32; ++i) { const int kk = 2 * i + (lane >> 5); wv_[i] = ok ? W[(size_t)(k0 + kk) * ldw + col] : 0.f; }
.LBB0_1682:
	s_ashr_i32 s2, s0, 31
	s_lshr_b32 s2, s2, 27
	s_add_i32 s2, s0, s2
	s_ashr_i32 s2, s2, 5
	s_lshl_b32 s3, s2, 10
	v_subrev_u32_e32 v4, s3, v10
	s_movk_i32 s3, 0x400
	v_cmp_gt_i32_e32 vcc, s3, v4
	s_lshl_b32 s6, s2, 6
	v_or_b32_e32 v6, s6, v8
	v_cndmask_b32_e32 v4, 0, v4, vcc
	v_ashrrev_i32_e32 v5, 31, v4
	v_lshl_add_u64 v[4:5], v[4:5], 2, s[4:5]
	v_mov_b32_e32 v13, 0
	v_mov_b32_e32 v7, 0
	s_and_saveexec_b64 s[8:9], vcc
	s_cbranch_execz .LBB0_1684
	v_ashrrev_i32_e32 v7, 31, v6
	v_lshlrev_b64 v[14:15], 12, v[6:7]
	v_lshl_add_u64 v[14:15], v[4:5], 0, v[14:15]
	global_load_dword v7, v[14:15], off nt
.LBB0_1684:
	s_or_b64 exec, exec, s[8:9]
	s_and_saveexec_b64 s[8:9], vcc
	s_cbranch_execz .LBB0_1686
	v_or_b32_e32 v14, 2, v6
	v_ashrrev_i32_e32 v15, 31, v14
	v_lshlrev_b64 v[14:15], 12, v[14:15]
	v_lshl_add_u64 v[14:15], v[4:5], 0, v[14:15]
	global_load_dword v13, v[14:15], off nt
.LBB0_1686:
	s_or_b64 exec, exec, s[8:9]
	v_mov_b32_e32 v14, 0
	v_mov_b32_e32 v15, 0
	s_and_saveexec_b64 s[8:9], vcc
	s_cbranch_execz .LBB0_1688
	v_or_b32_e32 v16, 4, v6
	v_ashrrev_i32_e32 v17, 31, v16
	v_lshlrev_b64 v[16:17], 12, v[16:17]
	v_lshl_add_u64 v[16:17], v[4:5], 0, v[16:17]
	global_load_dword v15, v[16:17], off nt
.LBB0_1688:
	s_or_b64 exec, exec, s[8:9]
	s_and_saveexec_b64 s[8:9], vcc
	s_cbranch_execz .LBB0_1690
	v_or_b32_e32 v16, 6, v6
	v_ashrrev_i32_e32 v17, 31, v16
	v_lshlrev_b64 v[16:17], 12, v[16:17]
	v_lshl_add_u64 v[16:17], v[4:5], 0, v[16:17]
	global_load_dword v14, v[16:17], off nt
.LBB0_1690:
	s_or_b64 exec, exec, s[8:9]
	v_mov_b32_e32 v16, 0
	v_mov_b32_e32 v17, 0
	s_and_saveexec_b64 s[8:9], vcc
	s_cbranch_execz .LBB0_1692
	v_or_b32_e32 v18, 8, v6
	v_ashrrev_i32_e32 v19, 31, v18
	v_lshlrev_b64 v[18:19], 12, v[18:19]
	v_lshl_add_u64 v[18:19], v[4:5], 0, v[18:19]
	global_load_dword v17, v[18:19], off nt
.LBB0_1692:
	s_or_b64 exec, exec, s[8:9]
	s_and_saveexec_b64 s[8:9], vcc
	s_cbranch_execz .LBB0_1694
	v_or_b32_e32 v18, 10, v6
	v_ashrrev_i32_e32 v19, 31, v18
	v_lshlrev_b64 v[18:19], 12, v[18:19]
	v_lshl_add_u64 v[18:19], v[4:5], 0, v[18:19]
	global_load_dword v16, v[18:19], off nt
.LBB0_1694:
	s_or_b64 exec, exec, s[8:9]
	v_mov_b32_e32 v18, 0
	v_mov_b32_e32 v19, 0
	s_and_saveexec_b64 s[8:9], vcc
	s_cbranch_execz .LBB0_1696
	v_or_b32_e32 v20, 12, v6
	v_ashrrev_i32_e32 v21, 31, v20
	v_lshlrev_b64 v[20:21], 12, v[20:21]
	v_lshl_add_u64 v[20:21], v[4:5], 0, v[20:21]
	global_load_dword v19, v[20:21], off nt
.LBB0_1696:
	s_or_b64 exec, exec, s[8:9]
	s_and_saveexec_b64 s[8:9], vcc
	s_cbranch_execz .LBB0_1698
	v_or_b32_e32 v20, 14, v6
	v_ashrrev_i32_e32 v21, 31, v20
	v_lshlrev_b64 v[20:21], 12, v[20:21]
	v_lshl_add_u64 v[20:21], v[4:5], 0, v[20:21]
	global_load_dword v18, v[20:21], off nt
.LBB0_1698:
	s_or_b64 exec, exec, s[8:9]
	v_mov_b32_e32 v20, 0
	v_mov_b32_e32 v21, 0
	s_and_saveexec_b64 s[8:9], vcc
	s_cbranch_execz .LBB0_1700
	v_or_b32_e32 v22, 16, v6
	v_ashrrev_i32_e32 v23, 31, v22
	v_lshlrev_b64 v[22:23], 12, v[22:23]
	v_lshl_add_u64 v[22:23], v[4:5], 0, v[22:23]
	global_load_dword v21, v[22:23], off nt
.LBB0_1700:
	s_or_b64 exec, exec, s[8:9]
	s_and_saveexec_b64 s[8:9], vcc
	s_cbranch_execz .LBB0_1702
	v_or_b32_e32 v22, 18, v6
	v_ashrrev_i32_e32 v23, 31, v22
	v_lshlrev_b64 v[22:23], 12, v[22:23]
	v_lshl_add_u64 v[22:23], v[4:5], 0, v[22:23]
	global_load_dword v20, v[22:23], off nt
.LBB0_1702:
	s_or_b64 exec, exec, s[8:9]
	v_mov_b32_e32 v22, 0
	v_mov_b32_e32 v23, 0
	s_and_saveexec_b64 s[8:9], vcc
	s_cbranch_execz .LBB0_1704
	v_or_b32_e32 v24, 20, v6
	v_ashrrev_i32_e32 v25, 31, v24
	v_lshlrev_b64 v[24:25], 12, v[24:25]
	v_lshl_add_u64 v[24:25], v[4:5], 0, v[24:25]
	global_load_dword v23, v[24:25], off nt
.LBB0_1704:
	s_or_b64 exec, exec, s[8:9]
	s_and_saveexec_b64 s[8:9], vcc
	s_cbranch_execz .LBB0_1706
	v_or_b32_e32 v24, 22, v6
	v_ashrrev_i32_e32 v25, 31, v24
	v_lshlrev_b64 v[24:25], 12, v[24:25]
	v_lshl_add_u64 v[24:25], v[4:5], 0, v[24:25]
	global_load_dword v22, v[24:25], off nt
.LBB0_1706:
	s_or_b64 exec, exec, s[8:9]
	v_mov_b32_e32 v24, 0
	v_mov_b32_e32 v25, 0
	s_and_saveexec_b64 s[8:9], vcc
	s_cbranch_execz .LBB0_1708
	v_or_b32_e32 v26, 24, v6
	v_ashrrev_i32_e32 v27, 31, v26
	v_lshlrev_b64 v[26:27], 12, v[26:27]
	v_lshl_add_u64 v[26:27], v[4:5], 0, v[26:27]
	global_load_dword v25, v[26:27], off nt
.LBB0_1708:
	s_or_b64 exec, exec, s[8:9]
	s_and_saveexec_b64 s[8:9], vcc
	s_cbranch_execz .LBB0_1710
	v_or_b32_e32 v26, 26, v6
	v_ashrrev_i32_e32 v27, 31, v26
	v_lshlrev_b64 v[26:27], 12, v[26:27]
	v_lshl_add_u64 v[26:27], v[4:5], 0, v[26:27]
	global_load_dword v24, v[26:27], off nt
.LBB0_1710:
	s_or_b64 exec, exec, s[8:9]
	v_mov_b32_e32 v26, 0
	v_mov_b32_e32 v27, 0
	s_and_saveexec_b64 s[8:9], vcc
	s_cbranch_execz .LBB0_1712
	v_or_b32_e32 v28, 28, v6
	v_ashrrev_i32_e32 v29, 31, v28
	v_lshlrev_b64 v[28:29], 12, v[28:29]
	v_lshl_add_u64 v[28:29], v[4:5], 0, v[28:29]
	global_load_dword v27, v[28:29], off nt
.LBB0_1712:
	s_or_b64 exec, exec, s[8:9]
	s_and_saveexec_b64 s[8:9], vcc
	s_cbranch_execz .LBB0_1714
	v_or_b32_e32 v28, 30, v6
	v_ashrrev_i32_e32 v29, 31, v28
	v_lshlrev_b64 v[28:29], 12, v[28:29]
	v_lshl_add_u64 v[28:29], v[4:5], 0, v[28:29]
	global_load_dword v26, v[28:29], off nt
; __device__ __forceinline__ void conv_weight(const float* W, int ldw, int K, int Nphys, int Nvalid, int mode, const float* g, bf16_t* WT, LAS float* scr, int gw, int NGW, int lane, int& rot) {
;     ...
;         for (int i = 0; i < 32; ++i) { const int kk = 2 * i + (lane >> 5); wv_[i] = ok ? W[(size_t)(k0 + kk) * ldw + col] : 0.f; }
.LBB0_1714:
	s_or_b64 exec, exec, s[8:9]
	v_mov_b32_e32 v28, 0
	v_mov_b32_e32 v29, 0
	s_and_saveexec_b64 s[8:9], vcc
	s_cbranch_execz .LBB0_1716
	v_or_b32_e32 v30, 32, v6
	v_ashrrev_i32_e32 v31, 31, v30
	v_lshlrev_b64 v[30:31], 12, v[30:31]
	v_lshl_add_u64 v[30:31], v[4:5], 0, v[30:31]
	global_load_dword v29, v[30:31], off nt
.LBB0_1716:
	s_or_b64 exec, exec, s[8:9]
	s_and_saveexec_b64 s[8:9], vcc
	s_cbranch_execz .LBB0_1718
	v_or_b32_e32 v30, 34, v6
	v_ashrrev_i32_e32 v31, 31, v30
	v_lshlrev_b64 v[30:31], 12, v[30:31]
	v_lshl_add_u64 v[30:31], v[4:5], 0, v[30:31]
	global_load_dword v28, v[30:31], off nt
.LBB0_1718:
	s_or_b64 exec, exec, s[8:9]
	v_mov_b32_e32 v30, 0
	v_mov_b32_e32 v31, 0
	s_and_saveexec_b64 s[8:9], vcc
	s_cbranch_execz .LBB0_1720
	v_or_b32_e32 v32, 36, v6
	v_ashrrev_i32_e32 v33, 31, v32
	v_lshlrev_b64 v[32:33], 12, v[32:33]
	v_lshl_add_u64 v[32:33], v[4:5], 0, v[32:33]
	global_load_dword v31, v[32:33], off nt
.LBB0_1720:
	s_or_b64 exec, exec, s[8:9]
	s_and_saveexec_b64 s[8:9], vcc
	s_cbranch_execz .LBB0_1722
	v_or_b32_e32 v32, 38, v6
	v_ashrrev_i32_e32 v33, 31, v32
	v_lshlrev_b64 v[32:33], 12, v[32:33]
	v_lshl_add_u64 v[32:33], v[4:5], 0, v[32:33]
	global_load_dword v30, v[32:33], off nt
.LBB0_1722:
	s_or_b64 exec, exec, s[8:9]
	v_mov_b32_e32 v32, 0
	v_mov_b32_e32 v33, 0
	s_and_saveexec_b64 s[8:9], vcc
	s_cbranch_execz .LBB0_1724
	v_or_b32_e32 v34, 40, v6
	v_ashrrev_i32_e32 v35, 31, v34
	v_lshlrev_b64 v[34:35], 12, v[34:35]
	v_lshl_add_u64 v[34:35], v[4:5], 0, v[34:35]
	global_load_dword v33, v[34:35], off nt
.LBB0_1724:
	s_or_b64 exec, exec, s[8:9]
	s_and_saveexec_b64 s[8:9], vcc
	s_cbranch_execz .LBB0_1726
	v_or_b32_e32 v34, 42, v6
	v_ashrrev_i32_e32 v35, 31, v34
	v_lshlrev_b64 v[34:35], 12, v[34:35]
	v_lshl_add_u64 v[34:35], v[4:5], 0, v[34:35]
	global_load_dword v32, v[34:35], off nt
.LBB0_1726:
	s_or_b64 exec, exec, s[8:9]
	v_mov_b32_e32 v34, 0
	v_mov_b32_e32 v35, 0
	s_and_saveexec_b64 s[8:9], vcc
	s_cbranch_execz .LBB0_1728
	v_or_b32_e32 v36, 44, v6
	v_ashrrev_i32_e32 v37, 31, v36
	v_lshlrev_b64 v[36:37], 12, v[36:37]
	v_lshl_add_u64 v[36:37], v[4:5], 0, v[36:37]
	global_load_dword v35, v[36:37], off nt
.LBB0_1728:
	s_or_b64 exec, exec, s[8:9]
	s_and_saveexec_b64 s[8:9], vcc
	s_cbranch_execz .LBB0_1730
	v_or_b32_e32 v36, 46, v6
	v_ashrrev_i32_e32 v37, 31, v36
	v_lshlrev_b64 v[36:37], 12, v[36:37]
	v_lshl_add_u64 v[36:37], v[4:5], 0, v[36:37]
	global_load_dword v34, v[36:37], off nt
.LBB0_1730:
	s_or_b64 exec, exec, s[8:9]
	v_mov_b32_e32 v36, 0
	v_mov_b32_e32 v37, 0
	s_and_saveexec_b64 s[8:9], vcc
	s_cbranch_execz .LBB0_1732
	v_or_b32_e32 v38, 48, v6
	v_ashrrev_i32_e32 v39, 31, v38
	v_lshlrev_b64 v[38:39], 12, v[38:39]
	v_lshl_add_u64 v[38:39], v[4:5], 0, v[38:39]
	global_load_dword v37, v[38:39], off nt
.LBB0_1732:
	s_or_b64 exec, exec, s[8:9]
	s_and_saveexec_b64 s[8:9], vcc
	s_cbranch_execz .LBB0_1734
	v_or_b32_e32 v38, 50, v6
	v_ashrrev_i32_e32 v39, 31, v38
	v_lshlrev_b64 v[38:39], 12, v[38:39]
	v_lshl_add_u64 v[38:39], v[4:5], 0, v[38:39]
	global_load_dword v36, v[38:39], off nt
.LBB0_1734:
	s_or_b64 exec, exec, s[8:9]
	v_mov_b32_e32 v38, 0
	v_mov_b32_e32 v39, 0
	s_and_saveexec_b64 s[8:9], vcc
	s_cbranch_execz .LBB0_1736
	v_or_b32_e32 v40, 52, v6
	v_ashrrev_i32_e32 v41, 31, v40
	v_lshlrev_b64 v[40:41], 12, v[40:41]
	v_lshl_add_u64 v[40:41], v[4:5], 0, v[40:41]
	global_load_dword v39, v[40:41], off nt
.LBB0_1736:
	s_or_b64 exec, exec, s[8:9]
	s_and_saveexec_b64 s[8:9], vcc
	s_cbranch_execz .LBB0_1738
	v_or_b32_e32 v40, 54, v6
	v_ashrrev_i32_e32 v41, 31, v40
	v_lshlrev_b64 v[40:41], 12, v[40:41]
	v_lshl_add_u64 v[40:41], v[4:5], 0, v[40:41]
	global_load_dword v38, v[40:41], off nt
.LBB0_1738:
	s_or_b64 exec, exec, s[8:9]
	v_mov_b32_e32 v40, 0
	v_mov_b32_e32 v41, 0
	s_and_saveexec_b64 s[8:9], vcc
	s_cbranch_execz .LBB0_1740
	v_or_b32_e32 v42, 56, v6
	v_ashrrev_i32_e32 v43, 31, v42
	v_lshlrev_b64 v[42:43], 12, v[42:43]
	v_lshl_add_u64 v[42:43], v[4:5], 0, v[42:43]
	global_load_dword v41, v[42:43], off nt
.LBB0_1740:
	s_or_b64 exec, exec, s[8:9]
	s_and_saveexec_b64 s[8:9], vcc
	s_cbranch_execz .LBB0_1742
	v_or_b32_e32 v42, 58, v6
	v_ashrrev_i32_e32 v43, 31, v42
	v_lshlrev_b64 v[42:43], 12, v[42:43]
	v_lshl_add_u64 v[42:43], v[4:5], 0, v[42:43]
	global_load_dword v40, v[42:43], off nt
.LBB0_1742:
	s_or_b64 exec, exec, s[8:9]
	v_mov_b32_e32 v42, 0
	v_mov_b32_e32 v43, 0
	s_and_saveexec_b64 s[8:9], vcc
	s_cbranch_execz .LBB0_1744
	v_or_b32_e32 v44, 60, v6
	v_ashrrev_i32_e32 v45, 31, v44
	v_lshlrev_b64 v[44:45], 12, v[44:45]
	v_lshl_add_u64 v[44:45], v[4:5], 0, v[44:45]
	global_load_dword v43, v[44:45], off nt
.LBB0_1744:
	s_or_b64 exec, exec, s[8:9]
	s_and_saveexec_b64 s[8:9], vcc
	s_cbranch_execz .LBB0_1681
	v_or_b32_e32 v44, 62, v6
	v_ashrrev_i32_e32 v45, 31, v44
	v_lshlrev_b64 v[44:45], 12, v[44:45]
	v_lshl_add_u64 v[4:5], v[4:5], 0, v[44:45]
	global_load_dword v42, v[4:5], off nt
	s_branch .LBB0_1681

; __device__ __forceinline__ void conv_weight(const float* W, int ldw, int K, int Nphys, int Nvalid, int mode, const float* g, bf16_t* WT, LAS float* scr, int gw, int NGW, int lane, int& rot) {
;     ...
;         for (int i = 0; i < 32; ++i) { const int kk = 2 * i + (lane >> 5); float v = wv_[i]; if (g) v *= g[k0 + kk]; scr[kk * 33 + (lane & 31)] = v; }
.LBB0_1750:
	s_or_b64 exec, exec, s[10:11]
	v_ashrrev_i32_e32 v5, 31, v4
	v_lshl_add_u64 v[4:5], v[4:5], 2, s[6:7]
	global_load_dword v4, v[4:5], off nt
	v_add_u32_e32 v7, 0x400, v0
	s_ashr_i32 s9, s8, 31
	s_add_i32 s0, s0, s22
	s_add_i32 s1, s1, s2
	s_cmpk_lt_i32 s0, 0x600
	s_waitcnt vmcnt(0)
	v_mul_f32_e32 v6, v79, v4
	v_or_b32_e32 v4, s8, v15
	v_ashrrev_i32_e32 v5, 31, v4
	v_lshl_add_u64 v[4:5], v[4:5], 2, s[6:7]
	global_load_dword v4, v[4:5], off nt
	s_waitcnt vmcnt(0)
	v_mul_f32_e32 v4, v75, v4
	ds_write2_b32 v0, v6, v4 offset1:66
	v_or_b32_e32 v4, s8, v16
	v_ashrrev_i32_e32 v5, 31, v4
	v_lshl_add_u64 v[4:5], v[4:5], 2, s[6:7]
	global_load_dword v4, v[4:5], off nt
	s_waitcnt vmcnt(0)
	v_mul_f32_e32 v6, v78, v4
	v_or_b32_e32 v4, s8, v17
	v_ashrrev_i32_e32 v5, 31, v4
	v_lshl_add_u64 v[4:5], v[4:5], 2, s[6:7]
	global_load_dword v4, v[4:5], off nt
	s_waitcnt vmcnt(0)
	v_mul_f32_e32 v4, v74, v4
	ds_write2_b32 v0, v6, v4 offset0:132 offset1:198
	v_or_b32_e32 v4, s8, v18
	v_ashrrev_i32_e32 v5, 31, v4
	v_lshl_add_u64 v[4:5], v[4:5], 2, s[6:7]
	global_load_dword v4, v[4:5], off nt
	s_waitcnt vmcnt(0)
	v_mul_f32_e32 v6, v77, v4
	v_or_b32_e32 v4, s8, v19
	v_ashrrev_i32_e32 v5, 31, v4
	v_lshl_add_u64 v[4:5], v[4:5], 2, s[6:7]
	global_load_dword v4, v[4:5], off nt
	s_waitcnt vmcnt(0)
	v_mul_f32_e32 v4, v73, v4
	ds_write2_b32 v7, v6, v4 offset0:8 offset1:74
	v_or_b32_e32 v4, s8, v20
	v_ashrrev_i32_e32 v5, 31, v4
	v_lshl_add_u64 v[4:5], v[4:5], 2, s[6:7]
	global_load_dword v4, v[4:5], off nt
	s_waitcnt vmcnt(0)
	v_mul_f32_e32 v6, v76, v4
	v_or_b32_e32 v4, s8, v21
	v_ashrrev_i32_e32 v5, 31, v4
	v_lshl_add_u64 v[4:5], v[4:5], 2, s[6:7]
	global_load_dword v4, v[4:5], off nt
	s_waitcnt vmcnt(0)
	v_mul_f32_e32 v4, v67, v4
	ds_write2_b32 v7, v6, v4 offset0:140 offset1:206
	v_or_b32_e32 v4, s8, v22
	v_ashrrev_i32_e32 v5, 31, v4
	v_lshl_add_u64 v[4:5], v[4:5], 2, s[6:7]
	global_load_dword v4, v[4:5], off nt
	v_add_u32_e32 v7, 0x800, v0
	s_waitcnt vmcnt(0)
	v_mul_f32_e32 v6, v72, v4
	v_or_b32_e32 v4, s8, v23
	v_ashrrev_i32_e32 v5, 31, v4
	v_lshl_add_u64 v[4:5], v[4:5], 2, s[6:7]
	global_load_dword v4, v[4:5], off nt
	s_waitcnt vmcnt(0)
	v_mul_f32_e32 v4, v69, v4
	ds_write2_b32 v7, v6, v4 offset0:16 offset1:82
	v_or_b32_e32 v4, s8, v24
	v_ashrrev_i32_e32 v5, 31, v4
	v_lshl_add_u64 v[4:5], v[4:5], 2, s[6:7]
	global_load_dword v4, v[4:5], off nt
	s_waitcnt vmcnt(0)
	v_mul_f32_e32 v6, v71, v4
	v_or_b32_e32 v4, s8, v25
	v_ashrrev_i32_e32 v5, 31, v4
	v_lshl_add_u64 v[4:5], v[4:5], 2, s[6:7]
	global_load_dword v4, v[4:5], off nt
	s_waitcnt vmcnt(0)
	v_mul_f32_e32 v4, v66, v4
	ds_write2_b32 v7, v6, v4 offset0:148 offset1:214
	v_or_b32_e32 v4, s8, v26
	v_ashrrev_i32_e32 v5, 31, v4
	v_lshl_add_u64 v[4:5], v[4:5], 2, s[6:7]
	global_load_dword v4, v[4:5], off nt
	v_add_u32_e32 v7, 0xc00, v0
	v_add_u32_e32 v66, s3, v10
	v_ashrrev_i32_e32 v67, 31, v66
	s_waitcnt vmcnt(0)
	v_mul_f32_e32 v6, v70, v4
	v_or_b32_e32 v4, s8, v27
	v_ashrrev_i32_e32 v5, 31, v4
	v_lshl_add_u64 v[4:5], v[4:5], 2, s[6:7]
	global_load_dword v4, v[4:5], off nt
	s_waitcnt vmcnt(0)
	v_mul_f32_e32 v4, v65, v4
	ds_write2_b32 v7, v6, v4 offset0:24 offset1:90
	v_or_b32_e32 v4, s8, v28
	v_ashrrev_i32_e32 v5, 31, v4
	v_lshl_add_u64 v[4:5], v[4:5], 2, s[6:7]
	global_load_dword v4, v[4:5], off nt
	s_waitcnt vmcnt(0)
	v_mul_f32_e32 v6, v68, v4
	v_or_b32_e32 v4, s8, v29
	v_ashrrev_i32_e32 v5, 31, v4
	v_lshl_add_u64 v[4:5], v[4:5], 2, s[6:7]
	global_load_dword v4, v[4:5], off nt
	v_lshlrev_b64 v[68:69], 11, v[66:67]
	s_waitcnt vmcnt(0)
	v_mul_f32_e32 v4, v59, v4
	ds_write2_b32 v7, v6, v4 offset0:156 offset1:222
	v_or_b32_e32 v4, s8, v30
	v_ashrrev_i32_e32 v5, 31, v4
	v_lshl_add_u64 v[4:5], v[4:5], 2, s[6:7]
	global_load_dword v4, v[4:5], off nt
	v_add_u32_e32 v7, 0x1000, v0
	s_waitcnt vmcnt(0)
	v_mul_f32_e32 v6, v64, v4
	v_or_b32_e32 v4, s8, v31
	v_ashrrev_i32_e32 v5, 31, v4
	v_lshl_add_u64 v[4:5], v[4:5], 2, s[6:7]
	global_load_dword v4, v[4:5], off nt
	s_waitcnt vmcnt(0)
	v_mul_f32_e32 v4, v61, v4
	ds_write2_b32 v7, v6, v4 offset0:32 offset1:98
	v_or_b32_e32 v4, s8, v32
	v_ashrrev_i32_e32 v5, 31, v4
	v_lshl_add_u64 v[4:5], v[4:5], 2, s[6:7]
	global_load_dword v4, v[4:5], off nt
	s_waitcnt vmcnt(0)
	v_mul_f32_e32 v6, v63, v4
	v_or_b32_e32 v4, s8, v33
	v_ashrrev_i32_e32 v5, 31, v4
	v_lshl_add_u64 v[4:5], v[4:5], 2, s[6:7]
	global_load_dword v4, v[4:5], off nt
	s_waitcnt vmcnt(0)
	v_mul_f32_e32 v4, v58, v4
	ds_write2_b32 v7, v6, v4 offset0:164 offset1:230
	v_or_b32_e32 v4, s8, v34
	v_ashrrev_i32_e32 v5, 31, v4
	v_lshl_add_u64 v[4:5], v[4:5], 2, s[6:7]
	global_load_dword v4, v[4:5], off nt
	v_add_u32_e32 v7, 0x1400, v0
	s_waitcnt vmcnt(0)
	v_mul_f32_e32 v6, v62, v4
	v_or_b32_e32 v4, s8, v35
	v_ashrrev_i32_e32 v5, 31, v4
	v_lshl_add_u64 v[4:5], v[4:5], 2, s[6:7]
	global_load_dword v4, v[4:5], off nt
	s_waitcnt vmcnt(0)
	v_mul_f32_e32 v4, v57, v4
	ds_write2_b32 v7, v6, v4 offset0:40 offset1:106
	v_or_b32_e32 v4, s8, v36
	v_ashrrev_i32_e32 v5, 31, v4
	v_lshl_add_u64 v[4:5], v[4:5], 2, s[6:7]
	global_load_dword v4, v[4:5], off nt
	s_waitcnt vmcnt(0)
	v_mul_f32_e32 v6, v60, v4
	v_or_b32_e32 v4, s8, v37
	v_ashrrev_i32_e32 v5, 31, v4
	v_lshl_add_u64 v[4:5], v[4:5], 2, s[6:7]
	global_load_dword v4, v[4:5], off nt
	s_waitcnt vmcnt(0)
	v_mul_f32_e32 v4, v52, v4
	ds_write2_b32 v7, v6, v4 offset0:172 offset1:238
	v_or_b32_e32 v4, s8, v38
	v_ashrrev_i32_e32 v5, 31, v4
	v_lshl_add_u64 v[4:5], v[4:5], 2, s[6:7]
	global_load_dword v4, v[4:5], off nt
	v_add_u32_e32 v7, 0x1800, v0
	s_waitcnt vmcnt(0)
	v_mul_f32_e32 v6, v56, v4
	v_or_b32_e32 v4, s8, v39
	v_ashrrev_i32_e32 v5, 31, v4
	v_lshl_add_u64 v[4:5], v[4:5], 2, s[6:7]
	global_load_dword v4, v[4:5], off nt
	s_waitcnt vmcnt(0)
; #define LAS __attribute__((address_space(3)))
; __device__ __forceinline__ unsigned pk2(float lo, float hi) { return f2bf(lo) | (f2bf(hi) << 16); }
; __device__ __forceinline__ void conv_weight(const float* W, int ldw, int K, int Nphys, int Nvalid, int mode, const float* g, bf16_t* WT, LAS float* scr, int gw, int NGW, int lane, int& rot) {
;     ...
;         for (int i = 0; i < 32; ++i) { const int kk = 2 * i + (lane >> 5); float v = wv_[i]; if (g) v *= g[k0 + kk]; scr[kk * 33 + (lane & 31)] = v; }
;         asm volatile("s_waitcnt lgkmcnt(0)" ::: "memory");
;         const int c = lane & 7;
; #pragma unroll
;         for (int j = 0; j < 4; ++j) { const int n = (lane >> 3) + 8 * j; const LAS float* s = scr + (8 * c) * 33 + n;
;             u32x4 o; o.x = pk2(s[0 * 33], s[1 * 33]); o.y = pk2(s[2 * 33], s[3 * 33]); o.z = pk2(s[4 * 33], s[5 * 33]); o.w = pk2(s[6 * 33], s[7 * 33]);
;             *(u32x4*)(WT + (size_t)(n0 + n) * K + k0 + 8 * c) = o; }
;         asm volatile("s_waitcnt lgkmcnt(0)" ::: "memory");
	v_mul_f32_e32 v4, v53, v4
	ds_write2_b32 v7, v6, v4 offset0:48 offset1:114
	v_or_b32_e32 v4, s8, v40
	v_ashrrev_i32_e32 v5, 31, v4
	v_lshl_add_u64 v[4:5], v[4:5], 2, s[6:7]
	global_load_dword v4, v[4:5], off nt
	s_waitcnt vmcnt(0)
	v_mul_f32_e32 v6, v55, v4
	v_or_b32_e32 v4, s8, v41
	v_ashrrev_i32_e32 v5, 31, v4
	v_lshl_add_u64 v[4:5], v[4:5], 2, s[6:7]
	global_load_dword v4, v[4:5], off nt
	s_waitcnt vmcnt(0)
	v_mul_f32_e32 v4, v51, v4
	ds_write2_b32 v7, v6, v4 offset0:180 offset1:246
	v_or_b32_e32 v4, s8, v42
	v_ashrrev_i32_e32 v5, 31, v4
	v_lshl_add_u64 v[4:5], v[4:5], 2, s[6:7]
	global_load_dword v4, v[4:5], off nt
	v_add_u32_e32 v7, 0x1c00, v0
	s_waitcnt vmcnt(0)
	v_mul_f32_e32 v6, v54, v4
	v_or_b32_e32 v4, s8, v43
	v_ashrrev_i32_e32 v5, 31, v4
	v_lshl_add_u64 v[4:5], v[4:5], 2, s[6:7]
	global_load_dword v4, v[4:5], off nt
	s_waitcnt vmcnt(0)
	v_mul_f32_e32 v4, v49, v4
	ds_write2_b32 v7, v6, v4 offset0:56 offset1:122
	v_or_b32_e32 v4, s8, v44
	v_ashrrev_i32_e32 v5, 31, v4
	v_lshl_add_u64 v[4:5], v[4:5], 2, s[6:7]
	global_load_dword v4, v[4:5], off nt
	s_waitcnt vmcnt(0)
	v_mul_f32_e32 v6, v50, v4
	v_or_b32_e32 v4, s8, v45
	v_ashrrev_i32_e32 v5, 31, v4
	v_lshl_add_u64 v[4:5], v[4:5], 2, s[6:7]
	global_load_dword v4, v[4:5], off nt
	s_waitcnt vmcnt(0)
	v_mul_f32_e32 v4, v48, v4
	ds_write2_b32 v7, v6, v4 offset0:188 offset1:254
	s_waitcnt lgkmcnt(0)
	ds_read2_b32 v[6:7], v47 offset0:33 offset1:41
	ds_read2_b32 v[52:53], v47 offset1:8
	ds_read2_b32 v[54:55], v47 offset0:66 offset1:74
	ds_read2_b32 v[56:57], v47 offset0:99 offset1:107
	v_lshl_add_u64 v[4:5], s[8:9], 1, v[2:3]
	s_mov_b32 s8, 0xffff0000
	s_waitcnt lgkmcnt(3)
	v_bfe_u32 v49, v6, 16, 1
	s_waitcnt lgkmcnt(2)
	v_bfe_u32 v48, v52, 16, 1
	v_add3_u32 v48, v52, v48, s33
	v_lshrrev_b32_e32 v48, 16, v48
	v_add3_u32 v6, v6, v49, s33
	ds_read2_b32 v[58:59], v47 offset0:132 offset1:140
	ds_read2_b32 v[60:61], v47 offset0:165 offset1:173
	v_and_or_b32 v48, v6, s8, v48
	s_waitcnt lgkmcnt(3)
	v_bfe_u32 v6, v54, 16, 1
	v_add3_u32 v6, v54, v6, s33
	s_waitcnt lgkmcnt(2)
	v_bfe_u32 v49, v56, 16, 1
	v_lshrrev_b32_e32 v6, 16, v6
	v_add3_u32 v49, v56, v49, s33
	ds_read2_b32 v[62:63], v47 offset0:198 offset1:206
	ds_read2_b32 v[64:65], v47 offset0:231 offset1:239
	v_and_or_b32 v49, v49, s8, v6
	s_waitcnt lgkmcnt(3)
	v_bfe_u32 v6, v58, 16, 1
	v_add3_u32 v6, v58, v6, s33
	s_waitcnt lgkmcnt(2)
	v_bfe_u32 v50, v60, 16, 1
	v_lshrrev_b32_e32 v6, 16, v6
	v_add3_u32 v50, v60, v50, s33
	v_and_or_b32 v50, v50, s8, v6
	s_waitcnt lgkmcnt(1)
	v_bfe_u32 v6, v62, 16, 1
	v_add3_u32 v6, v62, v6, s33
	s_waitcnt lgkmcnt(0)
	v_bfe_u32 v51, v64, 16, 1
	v_lshrrev_b32_e32 v6, 16, v6
	v_add3_u32 v51, v64, v51, s33
	v_and_or_b32 v51, v51, s8, v6
	v_lshl_add_u64 v[68:69], v[4:5], 0, v[68:69]
	v_bfe_u32 v6, v53, 16, 1
	global_store_dwordx4 v[68:69], v[48:51], off
	v_add3_u32 v6, v53, v6, s33
	v_lshrrev_b32_e32 v6, 16, v6
	v_bfe_u32 v48, v7, 16, 1
	v_add3_u32 v7, v7, v48, s33
	v_and_or_b32 v48, v7, s8, v6
	v_bfe_u32 v6, v55, 16, 1
	v_add3_u32 v6, v55, v6, s33
	v_bfe_u32 v7, v57, 16, 1
	v_lshrrev_b32_e32 v6, 16, v6
	v_add3_u32 v7, v57, v7, s33
	v_and_or_b32 v49, v7, s8, v6
	v_bfe_u32 v6, v59, 16, 1
	v_add3_u32 v6, v59, v6, s33
	v_bfe_u32 v7, v61, 16, 1
	v_lshrrev_b32_e32 v6, 16, v6
	v_add3_u32 v7, v61, v7, s33
	v_and_or_b32 v50, v7, s8, v6
	v_bfe_u32 v6, v63, 16, 1
	v_add3_u32 v6, v63, v6, s33
	v_bfe_u32 v7, v65, 16, 1
	v_lshrrev_b32_e32 v6, 16, v6
	v_add3_u32 v7, v65, v7, s33
	v_and_or_b32 v51, v7, s8, v6
	v_add_u32_e32 v6, 8, v66
	v_ashrrev_i32_e32 v7, 31, v6
	v_lshlrev_b64 v[6:7], 11, v[6:7]
	v_lshl_add_u64 v[6:7], v[4:5], 0, v[6:7]
	global_store_dwordx4 v[6:7], v[48:51], off
	ds_read2_b32 v[6:7], v47 offset0:49 offset1:57
	ds_read2_b32 v[52:53], v47 offset0:16 offset1:24
	ds_read2_b32 v[54:55], v47 offset0:82 offset1:90
	ds_read2_b32 v[56:57], v47 offset0:115 offset1:123
	ds_read2_b32 v[58:59], v47 offset0:148 offset1:156
	ds_read2_b32 v[60:61], v47 offset0:181 offset1:189
	ds_read2_b32 v[62:63], v47 offset0:214 offset1:222
	ds_read2_b32 v[64:65], v47 offset0:247 offset1:255
	s_waitcnt lgkmcnt(7)
	v_bfe_u32 v49, v6, 16, 1
	s_waitcnt lgkmcnt(6)
	v_bfe_u32 v48, v52, 16, 1
	v_add3_u32 v48, v52, v48, s33
	v_lshrrev_b32_e32 v48, 16, v48
	v_add3_u32 v6, v6, v49, s33
	v_and_or_b32 v48, v6, s8, v48
	s_waitcnt lgkmcnt(5)
	v_bfe_u32 v6, v54, 16, 1
	v_add3_u32 v6, v54, v6, s33
	s_waitcnt lgkmcnt(4)
	v_bfe_u32 v49, v56, 16, 1
	v_lshrrev_b32_e32 v6, 16, v6
	v_add3_u32 v49, v56, v49, s33
	v_and_or_b32 v49, v49, s8, v6
	s_waitcnt lgkmcnt(3)
	v_bfe_u32 v6, v58, 16, 1
	v_add3_u32 v6, v58, v6, s33
	s_waitcnt lgkmcnt(2)
	v_bfe_u32 v50, v60, 16, 1
	v_lshrrev_b32_e32 v6, 16, v6
	v_add3_u32 v50, v60, v50, s33
	v_and_or_b32 v50, v50, s8, v6
	s_waitcnt lgkmcnt(1)
	v_bfe_u32 v6, v62, 16, 1
	v_add_u32_e32 v68, 16, v66
	v_add3_u32 v6, v62, v6, s33
	s_waitcnt lgkmcnt(0)
	v_bfe_u32 v51, v64, 16, 1
	v_ashrrev_i32_e32 v69, 31, v68
	v_lshrrev_b32_e32 v6, 16, v6
	v_add3_u32 v51, v64, v51, s33
	v_lshlrev_b64 v[68:69], 11, v[68:69]
	v_and_or_b32 v51, v51, s8, v6
	v_lshl_add_u64 v[68:69], v[4:5], 0, v[68:69]
	v_bfe_u32 v6, v53, 16, 1
	global_store_dwordx4 v[68:69], v[48:51], off
	v_add3_u32 v6, v53, v6, s33
	v_lshrrev_b32_e32 v6, 16, v6
	v_bfe_u32 v48, v7, 16, 1
	v_add3_u32 v7, v7, v48, s33
	v_and_or_b32 v48, v7, s8, v6
	v_bfe_u32 v6, v55, 16, 1
	v_add3_u32 v6, v55, v6, s33
	v_bfe_u32 v7, v57, 16, 1
	v_lshrrev_b32_e32 v6, 16, v6
	v_add3_u32 v7, v57, v7, s33
	v_and_or_b32 v49, v7, s8, v6
	v_bfe_u32 v6, v59, 16, 1
	v_add3_u32 v6, v59, v6, s33
	v_bfe_u32 v7, v61, 16, 1
	v_lshrrev_b32_e32 v6, 16, v6
	v_add3_u32 v7, v61, v7, s33
	v_and_or_b32 v50, v7, s8, v6
	v_bfe_u32 v6, v63, 16, 1
	v_add3_u32 v6, v63, v6, s33
	v_bfe_u32 v7, v65, 16, 1
	v_lshrrev_b32_e32 v6, 16, v6
	v_add3_u32 v7, v65, v7, s33
	v_and_or_b32 v51, v7, s8, v6
	v_add_u32_e32 v6, 24, v66
	v_ashrrev_i32_e32 v7, 31, v6
	v_lshlrev_b64 v[6:7], 11, v[6:7]
	v_lshl_add_u64 v[4:5], v[4:5], 0, v[6:7]
	global_store_dwordx4 v[4:5], v[48:51], off
	s_waitcnt lgkmcnt(0)
	s_cbranch_scc0 .LBB0_1815
; __device__ __forceinline__ void conv_weight(const float* W, int ldw, int K, int Nphys, int Nvalid, int mode, const float* g, bf16_t* WT, LAS float* scr, int gw, int NGW, int lane, int& rot) {
;     ...
;         const int kb = it / nblk, nb = it % nblk, k0 = 64 * kb, n0 = 32 * nb;
;         const int prow = n0 + (lane & 31); const bool ok = prow < Nvalid; const int col = ok ? colmap(mode, prow) : 0;
;         float wv_[32];
; #pragma unroll
;         for (int i = 0; i < 32; ++i) { const int kk = 2 * i + (lane >> 5); wv_[i] = ok ? W[(size_t)(k0 + kk) * ldw + col] : 0.f; }
.LBB0_1751:
	s_mul_hi_i32 s3, s0, 0x2aaaaaab
	s_lshr_b32 s8, s3, 31
	s_ashr_i32 s3, s3, 4
	s_add_i32 s3, s3, s8
	s_lshl_b32 s8, s3, 6
	s_mulk_i32 s3, 0xf400
	s_add_i32 s3, s3, s1
	v_add_u32_e32 v4, s3, v8
	s_movk_i32 s9, 0xc00
	v_cmp_gt_i32_e32 vcc, s9, v4
	s_waitcnt vmcnt(5)
	v_mov_b32_e32 v75, 0
	s_waitcnt vmcnt(10)
	v_mov_b32_e32 v79, 0
	v_cndmask_b32_e32 v4, 0, v4, vcc
	v_ashrrev_i32_e32 v5, 31, v4
	v_lshl_add_u64 v[6:7], v[4:5], 2, s[4:5]
	v_or_b32_e32 v4, s8, v9
	s_and_saveexec_b64 s[10:11], vcc
	s_cbranch_execz .LBB0_1753
	s_movk_i32 s9, 0x3040
	v_mad_i64_i32 v[48:49], s[12:13], v4, s9, v[6:7]
	global_load_dword v79, v[48:49], off nt
.LBB0_1753:
	s_or_b64 exec, exec, s[10:11]
	s_and_saveexec_b64 s[10:11], vcc
	s_cbranch_execz .LBB0_1755
	v_or_b32_e32 v5, 2, v4
	s_movk_i32 s9, 0x3040
	v_mad_i64_i32 v[48:49], s[12:13], v5, s9, v[6:7]
	global_load_dword v75, v[48:49], off nt
.LBB0_1755:
	s_or_b64 exec, exec, s[10:11]
	v_mov_b32_e32 v74, 0
	v_mov_b32_e32 v78, 0
	s_and_saveexec_b64 s[10:11], vcc
	s_cbranch_execz .LBB0_1757
	v_or_b32_e32 v5, 4, v4
	s_movk_i32 s9, 0x3040
	v_mad_i64_i32 v[48:49], s[12:13], v5, s9, v[6:7]
	global_load_dword v78, v[48:49], off nt
.LBB0_1757:
	s_or_b64 exec, exec, s[10:11]
	s_and_saveexec_b64 s[10:11], vcc
	s_cbranch_execz .LBB0_1759
	v_or_b32_e32 v5, 6, v4
	s_movk_i32 s9, 0x3040
	v_mad_i64_i32 v[48:49], s[12:13], v5, s9, v[6:7]
	global_load_dword v74, v[48:49], off nt
.LBB0_1759:
	s_or_b64 exec, exec, s[10:11]
	s_waitcnt vmcnt(4)
	v_mov_b32_e32 v73, 0
	v_mov_b32_e32 v77, 0
	s_and_saveexec_b64 s[10:11], vcc
	s_cbranch_execz .LBB0_1761
	v_or_b32_e32 v5, 8, v4
	s_movk_i32 s9, 0x3040
	v_mad_i64_i32 v[48:49], s[12:13], v5, s9, v[6:7]
	global_load_dword v77, v[48:49], off nt
.LBB0_1761:
	s_or_b64 exec, exec, s[10:11]
	s_and_saveexec_b64 s[10:11], vcc
	s_cbranch_execz .LBB0_1763
	v_or_b32_e32 v5, 10, v4
	s_movk_i32 s9, 0x3040
	v_mad_i64_i32 v[48:49], s[12:13], v5, s9, v[6:7]
	global_load_dword v73, v[48:49], off nt
.LBB0_1763:
	s_or_b64 exec, exec, s[10:11]
	v_mov_b32_e32 v67, 0
	v_mov_b32_e32 v76, 0
	s_and_saveexec_b64 s[10:11], vcc
	s_cbranch_execz .LBB0_1765
	v_or_b32_e32 v5, 12, v4
	s_movk_i32 s9, 0x3040
	v_mad_i64_i32 v[48:49], s[12:13], v5, s9, v[6:7]
	global_load_dword v76, v[48:49], off nt
.LBB0_1765:
	s_or_b64 exec, exec, s[10:11]
	s_and_saveexec_b64 s[10:11], vcc
	s_cbranch_execz .LBB0_1767
	v_or_b32_e32 v5, 14, v4
	s_movk_i32 s9, 0x3040
	v_mad_i64_i32 v[48:49], s[12:13], v5, s9, v[6:7]
	global_load_dword v67, v[48:49], off nt
.LBB0_1767:
	s_or_b64 exec, exec, s[10:11]
	v_mov_b32_e32 v69, 0
	v_mov_b32_e32 v72, 0
	s_and_saveexec_b64 s[10:11], vcc
	s_cbranch_execz .LBB0_1769
	v_or_b32_e32 v5, 16, v4
	s_movk_i32 s9, 0x3040
	v_mad_i64_i32 v[48:49], s[12:13], v5, s9, v[6:7]
	global_load_dword v72, v[48:49], off nt
.LBB0_1769:
	s_or_b64 exec, exec, s[10:11]
	s_and_saveexec_b64 s[10:11], vcc
	s_cbranch_execz .LBB0_1771
	v_or_b32_e32 v5, 18, v4
	s_movk_i32 s9, 0x3040
	v_mad_i64_i32 v[48:49], s[12:13], v5, s9, v[6:7]
	global_load_dword v69, v[48:49], off nt
.LBB0_1771:
	s_or_b64 exec, exec, s[10:11]
	v_mov_b32_e32 v66, 0
	v_mov_b32_e32 v71, 0
	s_and_saveexec_b64 s[10:11], vcc
	s_cbranch_execz .LBB0_1773
	v_or_b32_e32 v5, 20, v4
	s_movk_i32 s9, 0x3040
	v_mad_i64_i32 v[48:49], s[12:13], v5, s9, v[6:7]
	global_load_dword v71, v[48:49], off nt
.LBB0_1773:
	s_or_b64 exec, exec, s[10:11]
	s_and_saveexec_b64 s[10:11], vcc
	s_cbranch_execz .LBB0_1775
	v_or_b32_e32 v5, 22, v4
	s_movk_i32 s9, 0x3040
	v_mad_i64_i32 v[48:49], s[12:13], v5, s9, v[6:7]
	global_load_dword v66, v[48:49], off nt
.LBB0_1775:
	s_or_b64 exec, exec, s[10:11]
	v_mov_b32_e32 v65, 0
	v_mov_b32_e32 v70, 0
	s_and_saveexec_b64 s[10:11], vcc
	s_cbranch_execz .LBB0_1777
	v_or_b32_e32 v5, 24, v4
	s_movk_i32 s9, 0x3040
	v_mad_i64_i32 v[48:49], s[12:13], v5, s9, v[6:7]
	global_load_dword v70, v[48:49], off nt
.LBB0_1777:
	s_or_b64 exec, exec, s[10:11]
	s_and_saveexec_b64 s[10:11], vcc
	s_cbranch_execz .LBB0_1779
	v_or_b32_e32 v5, 26, v4
	s_movk_i32 s9, 0x3040
	v_mad_i64_i32 v[48:49], s[12:13], v5, s9, v[6:7]
	global_load_dword v65, v[48:49], off nt
.LBB0_1779:
	s_or_b64 exec, exec, s[10:11]
	v_mov_b32_e32 v59, 0
	v_mov_b32_e32 v68, 0
	s_and_saveexec_b64 s[10:11], vcc
	s_cbranch_execz .LBB0_1781
	v_or_b32_e32 v5, 28, v4
	s_movk_i32 s9, 0x3040
	v_mad_i64_i32 v[48:49], s[12:13], v5, s9, v[6:7]
	global_load_dword v68, v[48:49], off nt
; __device__ __forceinline__ void conv_weight(const float* W, int ldw, int K, int Nphys, int Nvalid, int mode, const float* g, bf16_t* WT, LAS float* scr, int gw, int NGW, int lane, int& rot) {
;     ...
;         for (int i = 0; i < 32; ++i) { const int kk = 2 * i + (lane >> 5); wv_[i] = ok ? W[(size_t)(k0 + kk) * ldw + col] : 0.f; }
.LBB0_1781:
	s_or_b64 exec, exec, s[10:11]
	s_and_saveexec_b64 s[10:11], vcc
	s_cbranch_execz .LBB0_1783
	v_or_b32_e32 v5, 30, v4
	s_movk_i32 s9, 0x3040
	v_mad_i64_i32 v[48:49], s[12:13], v5, s9, v[6:7]
	global_load_dword v59, v[48:49], off nt
.LBB0_1783:
	s_or_b64 exec, exec, s[10:11]
	v_mov_b32_e32 v61, 0
	v_mov_b32_e32 v64, 0
	s_and_saveexec_b64 s[10:11], vcc
	s_cbranch_execz .LBB0_1785
	v_or_b32_e32 v5, 32, v4
	s_movk_i32 s9, 0x3040
	v_mad_i64_i32 v[48:49], s[12:13], v5, s9, v[6:7]
	global_load_dword v64, v[48:49], off nt
.LBB0_1785:
	s_or_b64 exec, exec, s[10:11]
	s_and_saveexec_b64 s[10:11], vcc
	s_cbranch_execz .LBB0_1787
	v_or_b32_e32 v5, 34, v4
	s_movk_i32 s9, 0x3040
	v_mad_i64_i32 v[48:49], s[12:13], v5, s9, v[6:7]
	global_load_dword v61, v[48:49], off nt
.LBB0_1787:
	s_or_b64 exec, exec, s[10:11]
	v_mov_b32_e32 v58, 0
	v_mov_b32_e32 v63, 0
	s_and_saveexec_b64 s[10:11], vcc
	s_cbranch_execz .LBB0_1789
	v_or_b32_e32 v5, 36, v4
	s_movk_i32 s9, 0x3040
	v_mad_i64_i32 v[48:49], s[12:13], v5, s9, v[6:7]
	global_load_dword v63, v[48:49], off nt
.LBB0_1789:
	s_or_b64 exec, exec, s[10:11]
	s_and_saveexec_b64 s[10:11], vcc
	s_cbranch_execz .LBB0_1791
	v_or_b32_e32 v5, 38, v4
	s_movk_i32 s9, 0x3040
	v_mad_i64_i32 v[48:49], s[12:13], v5, s9, v[6:7]
	global_load_dword v58, v[48:49], off nt
.LBB0_1791:
	s_or_b64 exec, exec, s[10:11]
	v_mov_b32_e32 v57, 0
	v_mov_b32_e32 v62, 0
	s_and_saveexec_b64 s[10:11], vcc
	s_cbranch_execz .LBB0_1793
	v_or_b32_e32 v5, 40, v4
	s_movk_i32 s9, 0x3040
	v_mad_i64_i32 v[48:49], s[12:13], v5, s9, v[6:7]
	global_load_dword v62, v[48:49], off nt
.LBB0_1793:
	s_or_b64 exec, exec, s[10:11]
	s_and_saveexec_b64 s[10:11], vcc
	s_cbranch_execz .LBB0_1795
	v_or_b32_e32 v5, 42, v4
	s_movk_i32 s9, 0x3040
	v_mad_i64_i32 v[48:49], s[12:13], v5, s9, v[6:7]
	global_load_dword v57, v[48:49], off nt
.LBB0_1795:
	s_or_b64 exec, exec, s[10:11]
	v_mov_b32_e32 v52, 0
	v_mov_b32_e32 v60, 0
	s_and_saveexec_b64 s[10:11], vcc
	s_cbranch_execz .LBB0_1797
	v_or_b32_e32 v5, 44, v4
	s_movk_i32 s9, 0x3040
	v_mad_i64_i32 v[48:49], s[12:13], v5, s9, v[6:7]
	global_load_dword v60, v[48:49], off nt
.LBB0_1797:
	s_or_b64 exec, exec, s[10:11]
	s_and_saveexec_b64 s[10:11], vcc
	s_cbranch_execz .LBB0_1799
	v_or_b32_e32 v5, 46, v4
	s_movk_i32 s9, 0x3040
	v_mad_i64_i32 v[48:49], s[12:13], v5, s9, v[6:7]
	global_load_dword v52, v[48:49], off nt
.LBB0_1799:
	s_or_b64 exec, exec, s[10:11]
	v_mov_b32_e32 v53, 0
	v_mov_b32_e32 v56, 0
	s_and_saveexec_b64 s[10:11], vcc
	s_cbranch_execz .LBB0_1801
	v_or_b32_e32 v5, 48, v4
	s_movk_i32 s9, 0x3040
	v_mad_i64_i32 v[48:49], s[12:13], v5, s9, v[6:7]
	global_load_dword v56, v[48:49], off nt
.LBB0_1801:
	s_or_b64 exec, exec, s[10:11]
	s_and_saveexec_b64 s[10:11], vcc
	s_cbranch_execz .LBB0_1803
	v_or_b32_e32 v5, 50, v4
	s_movk_i32 s9, 0x3040
	v_mad_i64_i32 v[48:49], s[12:13], v5, s9, v[6:7]
	global_load_dword v53, v[48:49], off nt
.LBB0_1803:
	s_or_b64 exec, exec, s[10:11]
	v_mov_b32_e32 v51, 0
	v_mov_b32_e32 v55, 0
	s_and_saveexec_b64 s[10:11], vcc
	s_cbranch_execz .LBB0_1805
	v_or_b32_e32 v5, 52, v4
	s_movk_i32 s9, 0x3040
	v_mad_i64_i32 v[48:49], s[12:13], v5, s9, v[6:7]
	global_load_dword v55, v[48:49], off nt
.LBB0_1805:
	s_or_b64 exec, exec, s[10:11]
	s_and_saveexec_b64 s[10:11], vcc
	s_cbranch_execz .LBB0_1807
	v_or_b32_e32 v5, 54, v4
	s_movk_i32 s9, 0x3040
	v_mad_i64_i32 v[48:49], s[12:13], v5, s9, v[6:7]
	global_load_dword v51, v[48:49], off nt
.LBB0_1807:
	s_or_b64 exec, exec, s[10:11]
	v_mov_b32_e32 v49, 0
	v_mov_b32_e32 v54, 0
	s_and_saveexec_b64 s[10:11], vcc
	s_cbranch_execz .LBB0_1809
	v_or_b32_e32 v5, 56, v4
	s_movk_i32 s9, 0x3040
	v_mad_i64_i32 v[80:81], s[12:13], v5, s9, v[6:7]
	global_load_dword v54, v[80:81], off nt
.LBB0_1809:
	s_or_b64 exec, exec, s[10:11]
	s_and_saveexec_b64 s[10:11], vcc
	s_cbranch_execz .LBB0_1811
	v_or_b32_e32 v5, 58, v4
	s_movk_i32 s9, 0x3040
	v_mad_i64_i32 v[48:49], s[12:13], v5, s9, v[6:7]
	global_load_dword v49, v[48:49], off nt
.LBB0_1811:
	s_or_b64 exec, exec, s[10:11]
	v_mov_b32_e32 v48, 0
	v_mov_b32_e32 v50, 0
	s_and_saveexec_b64 s[10:11], vcc
	s_cbranch_execz .LBB0_1813
	v_or_b32_e32 v5, 60, v4
	s_movk_i32 s9, 0x3040
	v_mad_i64_i32 v[80:81], s[12:13], v5, s9, v[6:7]
	global_load_dword v50, v[80:81], off nt
.LBB0_1813:
	s_or_b64 exec, exec, s[10:11]
	s_and_saveexec_b64 s[10:11], vcc
	s_cbranch_execz .LBB0_1750
	v_or_b32_e32 v5, 62, v4
	s_movk_i32 s9, 0x3040
	v_mad_i64_i32 v[6:7], s[12:13], v5, s9, v[6:7]
	global_load_dword v48, v[6:7], off nt
	s_branch .LBB0_1750

; __device__ __forceinline__ unsigned f2bf(float f) { unsigned u = __builtin_bit_cast(unsigned, f); return (u + 0x7fffu + ((u >> 16) & 1u)) >> 16; }
; #define INF(i) ((const float*)kin(i))
; #define WSP(T, off) ((T*)wsoff(off))
; __global__ void __launch_bounds__(512, 2) fwd_kernel(Args args) {
;     ...
;             { const float* wi = INF(9); const float* gm = INF(3) + 1024; bf16_t* wf = WSP(bf16_t, WS_WFT);
;               for (int idx = gt; idx < 32 * 1024; idx += NGT) { const int n = idx >> 10, k = idx & 1023; wf[idx] = (bf16_t)f2bf(n < 16 ? gm[k] * wi[(size_t)k * 3088 + 3072 + n] : 0.f); } }
.LBB0_1818:
	v_ashrrev_i32_e32 v6, 10, v2
	v_cmp_gt_i32_e32 vcc, 16, v6
	v_mov_b32_e32 v0, 0
	s_and_saveexec_b64 s[12:13], vcc
	s_cbranch_execz .LBB0_1817
	v_and_b32_e32 v0, 0x3ff, v2
	v_mov_b64_e32 v[46:47], s[6:7]
	s_movk_i32 s0, 0x3040
	v_ashrrev_i32_e32 v7, 31, v6
	v_mad_u64_u32 v[46:47], s[0:1], v0, s0, v[46:47]
	v_lshl_add_u64 v[6:7], v[6:7], 2, v[46:47]
	v_add_co_u32_e32 v6, vcc, 0x3000, v6
	v_lshlrev_b32_e32 v3, 2, v0
	s_nop 0
	v_addc_co_u32_e32 v7, vcc, 0, v7, vcc
	global_load_dword v3, v3, s[8:9]
	s_nop 0
	global_load_dword v0, v[6:7], off nt
	s_waitcnt vmcnt(0)
	v_mul_f32_e32 v0, v3, v0
	s_branch .LBB0_1817

; __device__ __forceinline__ void conv_weight(const float* W, int ldw, int K, int Nphys, int Nvalid, int mode, const float* g, bf16_t* WT, LAS float* scr, int gw, int NGW, int lane, int& rot) {
;     ...
;         const int kb = it / nblk, nb = it % nblk, k0 = 64 * kb, n0 = 32 * nb;
;         const int prow = n0 + (lane & 31); const bool ok = prow < Nvalid; const int col = ok ? colmap(mode, prow) : 0;
;         float wv_[32];
; #pragma unroll
;         for (int i = 0; i < 32; ++i) { const int kk = 2 * i + (lane >> 5); wv_[i] = ok ? W[(size_t)(k0 + kk) * ldw + col] : 0.f; }
.LBB0_1823:
	s_ashr_i32 s3, s0, 31
	s_lshr_b32 s3, s3, 27
	s_add_i32 s3, s0, s3
	s_ashr_i32 s3, s3, 5
	s_lshl_b32 s6, s3, 6
	s_lshl_b32 s3, s3, 10
	s_sub_i32 s7, s1, s3
	v_add_u32_e32 v4, s7, v8
	s_movk_i32 s7, 0x400
	v_cmp_gt_i32_e32 vcc, s7, v4
	v_or_b32_e32 v6, s6, v9
	v_mov_b32_e32 v47, 0
	v_cndmask_b32_e32 v4, 0, v4, vcc
	v_ashrrev_i32_e32 v5, 31, v4
	v_lshl_add_u64 v[4:5], v[4:5], 2, s[4:5]
	v_mov_b32_e32 v7, 0
	s_and_saveexec_b64 s[8:9], vcc
	s_cbranch_execz .LBB0_1825
	v_ashrrev_i32_e32 v7, 31, v6
	v_lshlrev_b64 v[48:49], 12, v[6:7]
	v_lshl_add_u64 v[48:49], v[4:5], 0, v[48:49]
	global_load_dword v7, v[48:49], off nt
.LBB0_1825:
	s_or_b64 exec, exec, s[8:9]
	s_and_saveexec_b64 s[8:9], vcc
	s_cbranch_execz .LBB0_1827
	v_or_b32_e32 v48, 2, v6
	v_ashrrev_i32_e32 v49, 31, v48
	v_lshlrev_b64 v[48:49], 12, v[48:49]
	v_lshl_add_u64 v[48:49], v[4:5], 0, v[48:49]
	global_load_dword v47, v[48:49], off nt
.LBB0_1827:
	s_or_b64 exec, exec, s[8:9]
	v_mov_b32_e32 v48, 0
	v_mov_b32_e32 v49, 0
	s_and_saveexec_b64 s[8:9], vcc
	s_cbranch_execz .LBB0_1829
	v_or_b32_e32 v50, 4, v6
	v_ashrrev_i32_e32 v51, 31, v50
	v_lshlrev_b64 v[50:51], 12, v[50:51]
	v_lshl_add_u64 v[50:51], v[4:5], 0, v[50:51]
	global_load_dword v49, v[50:51], off nt
.LBB0_1829:
	s_or_b64 exec, exec, s[8:9]
	s_and_saveexec_b64 s[8:9], vcc
	s_cbranch_execz .LBB0_1831
	v_or_b32_e32 v50, 6, v6
	v_ashrrev_i32_e32 v51, 31, v50
	v_lshlrev_b64 v[50:51], 12, v[50:51]
	v_lshl_add_u64 v[50:51], v[4:5], 0, v[50:51]
	global_load_dword v48, v[50:51], off nt
.LBB0_1831:
	s_or_b64 exec, exec, s[8:9]
	v_mov_b32_e32 v50, 0
	v_mov_b32_e32 v51, 0
	s_and_saveexec_b64 s[8:9], vcc
	s_cbranch_execz .LBB0_1833
	v_or_b32_e32 v52, 8, v6
	v_ashrrev_i32_e32 v53, 31, v52
	v_lshlrev_b64 v[52:53], 12, v[52:53]
	v_lshl_add_u64 v[52:53], v[4:5], 0, v[52:53]
	global_load_dword v51, v[52:53], off nt
.LBB0_1833:
	s_or_b64 exec, exec, s[8:9]
	s_and_saveexec_b64 s[8:9], vcc
	s_cbranch_execz .LBB0_1835
	v_or_b32_e32 v52, 10, v6
	v_ashrrev_i32_e32 v53, 31, v52
	v_lshlrev_b64 v[52:53], 12, v[52:53]
	v_lshl_add_u64 v[52:53], v[4:5], 0, v[52:53]
	global_load_dword v50, v[52:53], off nt
.LBB0_1835:
	s_or_b64 exec, exec, s[8:9]
	v_mov_b32_e32 v52, 0
	v_mov_b32_e32 v53, 0
	s_and_saveexec_b64 s[8:9], vcc
	s_cbranch_execz .LBB0_1837
	v_or_b32_e32 v54, 12, v6
	v_ashrrev_i32_e32 v55, 31, v54
	v_lshlrev_b64 v[54:55], 12, v[54:55]
	v_lshl_add_u64 v[54:55], v[4:5], 0, v[54:55]
	global_load_dword v53, v[54:55], off nt
.LBB0_1837:
	s_or_b64 exec, exec, s[8:9]
	s_and_saveexec_b64 s[8:9], vcc
	s_cbranch_execz .LBB0_1839
	v_or_b32_e32 v54, 14, v6
	v_ashrrev_i32_e32 v55, 31, v54
	v_lshlrev_b64 v[54:55], 12, v[54:55]
	v_lshl_add_u64 v[54:55], v[4:5], 0, v[54:55]
	global_load_dword v52, v[54:55], off nt
.LBB0_1839:
	s_or_b64 exec, exec, s[8:9]
	v_mov_b32_e32 v54, 0
	v_mov_b32_e32 v55, 0
	s_and_saveexec_b64 s[8:9], vcc
	s_cbranch_execz .LBB0_1841
	v_or_b32_e32 v56, 16, v6
	v_ashrrev_i32_e32 v57, 31, v56
	v_lshlrev_b64 v[56:57], 12, v[56:57]
	v_lshl_add_u64 v[56:57], v[4:5], 0, v[56:57]
	global_load_dword v55, v[56:57], off nt
.LBB0_1841:
	s_or_b64 exec, exec, s[8:9]
	s_and_saveexec_b64 s[8:9], vcc
	s_cbranch_execz .LBB0_1843
	v_or_b32_e32 v56, 18, v6
	v_ashrrev_i32_e32 v57, 31, v56
	v_lshlrev_b64 v[56:57], 12, v[56:57]
	v_lshl_add_u64 v[56:57], v[4:5], 0, v[56:57]
	global_load_dword v54, v[56:57], off nt
.LBB0_1843:
	s_or_b64 exec, exec, s[8:9]
	v_mov_b32_e32 v56, 0
	v_mov_b32_e32 v57, 0
	s_and_saveexec_b64 s[8:9], vcc
	s_cbranch_execz .LBB0_1845
	v_or_b32_e32 v58, 20, v6
	v_ashrrev_i32_e32 v59, 31, v58
	v_lshlrev_b64 v[58:59], 12, v[58:59]
	v_lshl_add_u64 v[58:59], v[4:5], 0, v[58:59]
	global_load_dword v57, v[58:59], off nt
.LBB0_1845:
	s_or_b64 exec, exec, s[8:9]
	s_and_saveexec_b64 s[8:9], vcc
	s_cbranch_execz .LBB0_1847
	v_or_b32_e32 v58, 22, v6
	v_ashrrev_i32_e32 v59, 31, v58
	v_lshlrev_b64 v[58:59], 12, v[58:59]
	v_lshl_add_u64 v[58:59], v[4:5], 0, v[58:59]
	global_load_dword v56, v[58:59], off nt
.LBB0_1847:
	s_or_b64 exec, exec, s[8:9]
	v_mov_b32_e32 v58, 0
	v_mov_b32_e32 v59, 0
	s_and_saveexec_b64 s[8:9], vcc
	s_cbranch_execz .LBB0_1849
	v_or_b32_e32 v60, 24, v6
	v_ashrrev_i32_e32 v61, 31, v60
	v_lshlrev_b64 v[60:61], 12, v[60:61]
	v_lshl_add_u64 v[60:61], v[4:5], 0, v[60:61]
	global_load_dword v59, v[60:61], off nt
.LBB0_1849:
	s_or_b64 exec, exec, s[8:9]
	s_and_saveexec_b64 s[8:9], vcc
	s_cbranch_execz .LBB0_1851
	v_or_b32_e32 v60, 26, v6
	v_ashrrev_i32_e32 v61, 31, v60
	v_lshlrev_b64 v[60:61], 12, v[60:61]
	v_lshl_add_u64 v[60:61], v[4:5], 0, v[60:61]
	global_load_dword v58, v[60:61], off nt
.LBB0_1851:
	s_or_b64 exec, exec, s[8:9]
	v_mov_b32_e32 v60, 0
	v_mov_b32_e32 v61, 0
	s_and_saveexec_b64 s[8:9], vcc
	s_cbranch_execz .LBB0_1853
	v_or_b32_e32 v62, 28, v6
	v_ashrrev_i32_e32 v63, 31, v62
	v_lshlrev_b64 v[62:63], 12, v[62:63]
	v_lshl_add_u64 v[62:63], v[4:5], 0, v[62:63]
	global_load_dword v61, v[62:63], off nt
.LBB0_1853:
	s_or_b64 exec, exec, s[8:9]
	s_and_saveexec_b64 s[8:9], vcc
	s_cbranch_execz .LBB0_1855
	v_or_b32_e32 v62, 30, v6
	v_ashrrev_i32_e32 v63, 31, v62
	v_lshlrev_b64 v[62:63], 12, v[62:63]
	v_lshl_add_u64 v[62:63], v[4:5], 0, v[62:63]
	global_load_dword v60, v[62:63], off nt
; __device__ __forceinline__ void conv_weight(const float* W, int ldw, int K, int Nphys, int Nvalid, int mode, const float* g, bf16_t* WT, LAS float* scr, int gw, int NGW, int lane, int& rot) {
;     ...
;         for (int i = 0; i < 32; ++i) { const int kk = 2 * i + (lane >> 5); wv_[i] = ok ? W[(size_t)(k0 + kk) * ldw + col] : 0.f; }
.LBB0_1855:
	s_or_b64 exec, exec, s[8:9]
	v_mov_b32_e32 v62, 0
	v_mov_b32_e32 v63, 0
	s_and_saveexec_b64 s[8:9], vcc
	s_cbranch_execz .LBB0_1857
	v_or_b32_e32 v64, 32, v6
	v_ashrrev_i32_e32 v65, 31, v64
	v_lshlrev_b64 v[64:65], 12, v[64:65]
	v_lshl_add_u64 v[64:65], v[4:5], 0, v[64:65]
	global_load_dword v63, v[64:65], off nt
.LBB0_1857:
	s_or_b64 exec, exec, s[8:9]
	s_and_saveexec_b64 s[8:9], vcc
	s_cbranch_execz .LBB0_1859
	v_or_b32_e32 v64, 34, v6
	v_ashrrev_i32_e32 v65, 31, v64
	v_lshlrev_b64 v[64:65], 12, v[64:65]
	v_lshl_add_u64 v[64:65], v[4:5], 0, v[64:65]
	global_load_dword v62, v[64:65], off nt
.LBB0_1859:
	s_or_b64 exec, exec, s[8:9]
	v_mov_b32_e32 v64, 0
	v_mov_b32_e32 v65, 0
	s_and_saveexec_b64 s[8:9], vcc
	s_cbranch_execz .LBB0_1861
	s_waitcnt vmcnt(7)
	v_or_b32_e32 v66, 36, v6
	v_ashrrev_i32_e32 v67, 31, v66
	v_lshlrev_b64 v[66:67], 12, v[66:67]
	v_lshl_add_u64 v[66:67], v[4:5], 0, v[66:67]
	global_load_dword v65, v[66:67], off nt
.LBB0_1861:
	s_or_b64 exec, exec, s[8:9]
	s_and_saveexec_b64 s[8:9], vcc
	s_cbranch_execz .LBB0_1863
	s_waitcnt vmcnt(7)
	v_or_b32_e32 v66, 38, v6
	v_ashrrev_i32_e32 v67, 31, v66
	v_lshlrev_b64 v[66:67], 12, v[66:67]
	v_lshl_add_u64 v[66:67], v[4:5], 0, v[66:67]
	global_load_dword v64, v[66:67], off nt
.LBB0_1863:
	s_or_b64 exec, exec, s[8:9]
	s_waitcnt vmcnt(7)
	v_mov_b32_e32 v66, 0
	v_mov_b32_e32 v67, 0
	s_and_saveexec_b64 s[8:9], vcc
	s_cbranch_execz .LBB0_1865
	v_or_b32_e32 v68, 40, v6
	v_ashrrev_i32_e32 v69, 31, v68
	v_lshlrev_b64 v[68:69], 12, v[68:69]
	v_lshl_add_u64 v[68:69], v[4:5], 0, v[68:69]
	global_load_dword v67, v[68:69], off nt
.LBB0_1865:
	s_or_b64 exec, exec, s[8:9]
	s_and_saveexec_b64 s[8:9], vcc
	s_cbranch_execz .LBB0_1867
	v_or_b32_e32 v68, 42, v6
	v_ashrrev_i32_e32 v69, 31, v68
	v_lshlrev_b64 v[68:69], 12, v[68:69]
	v_lshl_add_u64 v[68:69], v[4:5], 0, v[68:69]
	global_load_dword v66, v[68:69], off nt
.LBB0_1867:
	s_or_b64 exec, exec, s[8:9]
	v_mov_b32_e32 v68, 0
	v_mov_b32_e32 v69, 0
	s_and_saveexec_b64 s[8:9], vcc
	s_cbranch_execz .LBB0_1869
	s_waitcnt vmcnt(4)
	v_or_b32_e32 v70, 44, v6
	v_ashrrev_i32_e32 v71, 31, v70
	v_lshlrev_b64 v[70:71], 12, v[70:71]
	v_lshl_add_u64 v[70:71], v[4:5], 0, v[70:71]
	global_load_dword v69, v[70:71], off nt
.LBB0_1869:
	s_or_b64 exec, exec, s[8:9]
	s_and_saveexec_b64 s[8:9], vcc
	s_cbranch_execz .LBB0_1871
	s_waitcnt vmcnt(4)
	v_or_b32_e32 v70, 46, v6
	v_ashrrev_i32_e32 v71, 31, v70
	v_lshlrev_b64 v[70:71], 12, v[70:71]
	v_lshl_add_u64 v[70:71], v[4:5], 0, v[70:71]
	global_load_dword v68, v[70:71], off nt
.LBB0_1871:
	s_or_b64 exec, exec, s[8:9]
	s_waitcnt vmcnt(4)
	v_mov_b32_e32 v70, 0
	v_mov_b32_e32 v71, 0
	s_and_saveexec_b64 s[8:9], vcc
	s_cbranch_execz .LBB0_1873
	v_or_b32_e32 v72, 48, v6
	v_ashrrev_i32_e32 v73, 31, v72
	v_lshlrev_b64 v[72:73], 12, v[72:73]
	v_lshl_add_u64 v[72:73], v[4:5], 0, v[72:73]
	global_load_dword v71, v[72:73], off nt
.LBB0_1873:
	s_or_b64 exec, exec, s[8:9]
	s_and_saveexec_b64 s[8:9], vcc
	s_cbranch_execz .LBB0_1875
	v_or_b32_e32 v72, 50, v6
	v_ashrrev_i32_e32 v73, 31, v72
	v_lshlrev_b64 v[72:73], 12, v[72:73]
	v_lshl_add_u64 v[72:73], v[4:5], 0, v[72:73]
	global_load_dword v70, v[72:73], off nt
.LBB0_1875:
	s_or_b64 exec, exec, s[8:9]
	v_mov_b32_e32 v72, 0
	v_mov_b32_e32 v73, 0
	s_and_saveexec_b64 s[8:9], vcc
	s_cbranch_execz .LBB0_1877
	v_or_b32_e32 v74, 52, v6
	v_ashrrev_i32_e32 v75, 31, v74
	v_lshlrev_b64 v[74:75], 12, v[74:75]
	v_lshl_add_u64 v[74:75], v[4:5], 0, v[74:75]
	global_load_dword v73, v[74:75], off nt
.LBB0_1877:
	s_or_b64 exec, exec, s[8:9]
	s_and_saveexec_b64 s[8:9], vcc
	s_cbranch_execz .LBB0_1879
	v_or_b32_e32 v74, 54, v6
	v_ashrrev_i32_e32 v75, 31, v74
	v_lshlrev_b64 v[74:75], 12, v[74:75]
	v_lshl_add_u64 v[74:75], v[4:5], 0, v[74:75]
	global_load_dword v72, v[74:75], off nt
.LBB0_1879:
	s_or_b64 exec, exec, s[8:9]
	v_mov_b32_e32 v74, 0
	v_mov_b32_e32 v75, 0
	s_and_saveexec_b64 s[8:9], vcc
	s_cbranch_execz .LBB0_1881
	v_or_b32_e32 v76, 56, v6
	v_ashrrev_i32_e32 v77, 31, v76
	v_lshlrev_b64 v[76:77], 12, v[76:77]
	v_lshl_add_u64 v[76:77], v[4:5], 0, v[76:77]
	global_load_dword v75, v[76:77], off nt
.LBB0_1881:
	s_or_b64 exec, exec, s[8:9]
	s_and_saveexec_b64 s[8:9], vcc
	s_cbranch_execz .LBB0_1883
	v_or_b32_e32 v76, 58, v6
	v_ashrrev_i32_e32 v77, 31, v76
	v_lshlrev_b64 v[76:77], 12, v[76:77]
	v_lshl_add_u64 v[76:77], v[4:5], 0, v[76:77]
	global_load_dword v74, v[76:77], off nt
.LBB0_1883:
	s_or_b64 exec, exec, s[8:9]
	v_mov_b32_e32 v76, 0
	v_mov_b32_e32 v77, 0
	s_and_saveexec_b64 s[8:9], vcc
	s_cbranch_execz .LBB0_1885
	v_or_b32_e32 v78, 60, v6
	v_ashrrev_i32_e32 v79, 31, v78
	v_lshlrev_b64 v[78:79], 12, v[78:79]
	v_lshl_add_u64 v[78:79], v[4:5], 0, v[78:79]
	global_load_dword v77, v[78:79], off nt
.LBB0_1885:
	s_or_b64 exec, exec, s[8:9]
	s_and_saveexec_b64 s[8:9], vcc
	s_cbranch_execz .LBB0_1822
	v_or_b32_e32 v78, 62, v6
	v_ashrrev_i32_e32 v79, 31, v78
	v_lshlrev_b64 v[78:79], 12, v[78:79]
	v_lshl_add_u64 v[4:5], v[4:5], 0, v[78:79]
	global_load_dword v76, v[4:5], off nt
	s_branch .LBB0_1822

; __device__ __forceinline__ void conv_weight(const float* W, int ldw, int K, int Nphys, int Nvalid, int mode, const float* g, bf16_t* WT, LAS float* scr, int gw, int NGW, int lane, int& rot) {
;     ...
;         for (int i = 0; i < 32; ++i) { const int kk = 2 * i + (lane >> 5); float v = wv_[i]; if (g) v *= g[k0 + kk]; scr[kk * 33 + (lane & 31)] = v; }
.LBB0_1889:
	s_or_b64 exec, exec, s[10:11]
	v_lshl_add_u64 v[4:5], v[4:5], 2, s[6:7]
	global_load_dword v4, v[4:5], off nt
	v_add_u32_e32 v7, 0x400, v0
	s_ashr_i32 s9, s8, 31
	s_sub_i32 s3, 0, s3
	s_add_i32 s3, s3, s1
	s_add_i32 s0, s0, s22
	s_add_i32 s1, s1, s2
	s_cmpk_lt_i32 s0, 0x80
	s_waitcnt vmcnt(0)
	v_mul_f32_e32 v6, v75, v4
	v_or_b32_e32 v4, s8, v15
	v_ashrrev_i32_e32 v5, 31, v4
	v_lshl_add_u64 v[4:5], v[4:5], 2, s[6:7]
	global_load_dword v4, v[4:5], off nt
	s_waitcnt vmcnt(0)
	v_mul_f32_e32 v4, v68, v4
	ds_write2_b32 v0, v6, v4 offset1:66
	v_or_b32_e32 v4, s8, v16
	v_ashrrev_i32_e32 v5, 31, v4
	v_lshl_add_u64 v[4:5], v[4:5], 2, s[6:7]
	global_load_dword v4, v[4:5], off nt
	s_waitcnt vmcnt(0)
	v_mul_f32_e32 v6, v76, v4
	v_or_b32_e32 v4, s8, v17
	v_ashrrev_i32_e32 v5, 31, v4
	v_lshl_add_u64 v[4:5], v[4:5], 2, s[6:7]
	global_load_dword v4, v[4:5], off nt
	s_waitcnt vmcnt(0)
	v_mul_f32_e32 v4, v69, v4
	ds_write2_b32 v0, v6, v4 offset0:132 offset1:198
	v_or_b32_e32 v4, s8, v18
	v_ashrrev_i32_e32 v5, 31, v4
	v_lshl_add_u64 v[4:5], v[4:5], 2, s[6:7]
	global_load_dword v4, v[4:5], off nt
	s_waitcnt vmcnt(0)
	v_mul_f32_e32 v6, v78, v4
	v_or_b32_e32 v4, s8, v19
	v_ashrrev_i32_e32 v5, 31, v4
	v_lshl_add_u64 v[4:5], v[4:5], 2, s[6:7]
	global_load_dword v4, v[4:5], off nt
	s_waitcnt vmcnt(0)
	v_mul_f32_e32 v4, v71, v4
	ds_write2_b32 v7, v6, v4 offset0:8 offset1:74
	v_or_b32_e32 v4, s8, v20
	v_ashrrev_i32_e32 v5, 31, v4
	v_lshl_add_u64 v[4:5], v[4:5], 2, s[6:7]
	global_load_dword v4, v[4:5], off nt
	s_waitcnt vmcnt(0)
	v_mul_f32_e32 v6, v77, v4
	v_or_b32_e32 v4, s8, v21
	v_ashrrev_i32_e32 v5, 31, v4
	v_lshl_add_u64 v[4:5], v[4:5], 2, s[6:7]
	global_load_dword v4, v[4:5], off nt
	s_waitcnt vmcnt(0)
	v_mul_f32_e32 v4, v59, v4
	ds_write2_b32 v7, v6, v4 offset0:140 offset1:206
	v_or_b32_e32 v4, s8, v22
	v_ashrrev_i32_e32 v5, 31, v4
	v_lshl_add_u64 v[4:5], v[4:5], 2, s[6:7]
	global_load_dword v4, v[4:5], off nt
	v_add_u32_e32 v7, 0x800, v0
	s_waitcnt vmcnt(0)
	v_mul_f32_e32 v6, v72, v4
	v_or_b32_e32 v4, s8, v23
	v_ashrrev_i32_e32 v5, 31, v4
	v_lshl_add_u64 v[4:5], v[4:5], 2, s[6:7]
	global_load_dword v4, v[4:5], off nt
	s_waitcnt vmcnt(0)
	v_mul_f32_e32 v4, v62, v4
	ds_write2_b32 v7, v6, v4 offset0:16 offset1:82
	v_or_b32_e32 v4, s8, v24
	v_ashrrev_i32_e32 v5, 31, v4
	v_lshl_add_u64 v[4:5], v[4:5], 2, s[6:7]
	global_load_dword v4, v[4:5], off nt
	s_waitcnt vmcnt(0)
	v_mul_f32_e32 v6, v70, v4
	v_or_b32_e32 v4, s8, v25
	v_ashrrev_i32_e32 v5, 31, v4
	v_lshl_add_u64 v[4:5], v[4:5], 2, s[6:7]
	global_load_dword v4, v[4:5], off nt
	s_waitcnt vmcnt(0)
	v_mul_f32_e32 v4, v61, v4
	ds_write2_b32 v7, v6, v4 offset0:148 offset1:214
	v_or_b32_e32 v4, s8, v26
	v_ashrrev_i32_e32 v5, 31, v4
	v_lshl_add_u64 v[4:5], v[4:5], 2, s[6:7]
	global_load_dword v4, v[4:5], off nt
	v_add_u32_e32 v7, 0xc00, v0
	s_waitcnt vmcnt(0)
	v_mul_f32_e32 v6, v74, v4
	v_or_b32_e32 v4, s8, v27
	v_ashrrev_i32_e32 v5, 31, v4
	v_lshl_add_u64 v[4:5], v[4:5], 2, s[6:7]
	global_load_dword v4, v[4:5], off nt
	s_waitcnt vmcnt(0)
	v_mul_f32_e32 v4, v64, v4
	ds_write2_b32 v7, v6, v4 offset0:24 offset1:90
	v_or_b32_e32 v4, s8, v28
	v_ashrrev_i32_e32 v5, 31, v4
	v_lshl_add_u64 v[4:5], v[4:5], 2, s[6:7]
	global_load_dword v4, v[4:5], off nt
	s_waitcnt vmcnt(0)
	v_mul_f32_e32 v6, v73, v4
	v_or_b32_e32 v4, s8, v29
	v_ashrrev_i32_e32 v5, 31, v4
	v_lshl_add_u64 v[4:5], v[4:5], 2, s[6:7]
	global_load_dword v4, v[4:5], off nt
	s_waitcnt vmcnt(0)
	v_mul_f32_e32 v4, v52, v4
	ds_write2_b32 v7, v6, v4 offset0:156 offset1:222
	v_or_b32_e32 v4, s8, v30
	v_ashrrev_i32_e32 v5, 31, v4
	v_lshl_add_u64 v[4:5], v[4:5], 2, s[6:7]
	global_load_dword v4, v[4:5], off nt
	v_add_u32_e32 v7, 0x1000, v0
	s_waitcnt vmcnt(0)
	v_mul_f32_e32 v6, v65, v4
	v_or_b32_e32 v4, s8, v31
	v_ashrrev_i32_e32 v5, 31, v4
	v_lshl_add_u64 v[4:5], v[4:5], 2, s[6:7]
	global_load_dword v4, v[4:5], off nt
	s_waitcnt vmcnt(0)
	v_mul_f32_e32 v4, v55, v4
	ds_write2_b32 v7, v6, v4 offset0:32 offset1:98
	v_or_b32_e32 v4, s8, v32
	v_ashrrev_i32_e32 v5, 31, v4
	v_lshl_add_u64 v[4:5], v[4:5], 2, s[6:7]
	global_load_dword v4, v[4:5], off nt
	s_waitcnt vmcnt(0)
	v_mul_f32_e32 v6, v63, v4
	v_or_b32_e32 v4, s8, v33
	v_ashrrev_i32_e32 v5, 31, v4
	v_lshl_add_u64 v[4:5], v[4:5], 2, s[6:7]
	global_load_dword v4, v[4:5], off nt
	s_waitcnt vmcnt(0)
	v_mul_f32_e32 v4, v54, v4
	ds_write2_b32 v7, v6, v4 offset0:164 offset1:230
	v_or_b32_e32 v4, s8, v34
	v_ashrrev_i32_e32 v5, 31, v4
	v_lshl_add_u64 v[4:5], v[4:5], 2, s[6:7]
	global_load_dword v4, v[4:5], off nt
	v_add_u32_e32 v7, 0x1400, v0
	s_waitcnt vmcnt(0)
	v_mul_f32_e32 v6, v67, v4
	v_or_b32_e32 v4, s8, v35
	v_ashrrev_i32_e32 v5, 31, v4
	v_lshl_add_u64 v[4:5], v[4:5], 2, s[6:7]
	global_load_dword v4, v[4:5], off nt
	s_waitcnt vmcnt(0)
	v_mul_f32_e32 v4, v57, v4
	ds_write2_b32 v7, v6, v4 offset0:40 offset1:106
	v_or_b32_e32 v4, s8, v36
	v_ashrrev_i32_e32 v5, 31, v4
	v_lshl_add_u64 v[4:5], v[4:5], 2, s[6:7]
	global_load_dword v4, v[4:5], off nt
	s_waitcnt vmcnt(0)
	v_mul_f32_e32 v6, v66, v4
	v_or_b32_e32 v4, s8, v37
	v_ashrrev_i32_e32 v5, 31, v4
	v_lshl_add_u64 v[4:5], v[4:5], 2, s[6:7]
	global_load_dword v4, v[4:5], off nt
	v_add_u32_e32 v66, s3, v10
	v_ashrrev_i32_e32 v67, 31, v66
	v_lshlrev_b64 v[68:69], 11, v[66:67]
	s_waitcnt vmcnt(0)
	v_mul_f32_e32 v4, v49, v4
	ds_write2_b32 v7, v6, v4 offset0:172 offset1:238
	v_or_b32_e32 v4, s8, v38
	v_ashrrev_i32_e32 v5, 31, v4
	v_lshl_add_u64 v[4:5], v[4:5], 2, s[6:7]
	global_load_dword v4, v[4:5], off nt
	v_add_u32_e32 v7, 0x1800, v0
	s_waitcnt vmcnt(0)
	v_mul_f32_e32 v6, v58, v4
	v_or_b32_e32 v4, s8, v39
	v_ashrrev_i32_e32 v5, 31, v4
	v_lshl_add_u64 v[4:5], v[4:5], 2, s[6:7]
	global_load_dword v4, v[4:5], off nt
	s_waitcnt vmcnt(0)
; #define LAS __attribute__((address_space(3)))
; __device__ __forceinline__ unsigned pk2(float lo, float hi) { return f2bf(lo) | (f2bf(hi) << 16); }
; __device__ __forceinline__ void conv_weight(const float* W, int ldw, int K, int Nphys, int Nvalid, int mode, const float* g, bf16_t* WT, LAS float* scr, int gw, int NGW, int lane, int& rot) {
;     ...
;         for (int i = 0; i < 32; ++i) { const int kk = 2 * i + (lane >> 5); float v = wv_[i]; if (g) v *= g[k0 + kk]; scr[kk * 33 + (lane & 31)] = v; }
;         asm volatile("s_waitcnt lgkmcnt(0)" ::: "memory");
;         const int c = lane & 7;
; #pragma unroll
;         for (int j = 0; j < 4; ++j) { const int n = (lane >> 3) + 8 * j; const LAS float* s = scr + (8 * c) * 33 + n;
;             u32x4 o; o.x = pk2(s[0 * 33], s[1 * 33]); o.y = pk2(s[2 * 33], s[3 * 33]); o.z = pk2(s[4 * 33], s[5 * 33]); o.w = pk2(s[6 * 33], s[7 * 33]);
;             *(u32x4*)(WT + (size_t)(n0 + n) * K + k0 + 8 * c) = o; }
;         asm volatile("s_waitcnt lgkmcnt(0)" ::: "memory");
	v_mul_f32_e32 v4, v51, v4
	ds_write2_b32 v7, v6, v4 offset0:48 offset1:114
	v_or_b32_e32 v4, s8, v40
	v_ashrrev_i32_e32 v5, 31, v4
	v_lshl_add_u64 v[4:5], v[4:5], 2, s[6:7]
	global_load_dword v4, v[4:5], off nt
	s_waitcnt vmcnt(0)
	v_mul_f32_e32 v6, v56, v4
	v_or_b32_e32 v4, s8, v41
	v_ashrrev_i32_e32 v5, 31, v4
	v_lshl_add_u64 v[4:5], v[4:5], 2, s[6:7]
	global_load_dword v4, v[4:5], off nt
	s_waitcnt vmcnt(0)
	v_mul_f32_e32 v4, v50, v4
	ds_write2_b32 v7, v6, v4 offset0:180 offset1:246
	v_or_b32_e32 v4, s8, v42
	v_ashrrev_i32_e32 v5, 31, v4
	v_lshl_add_u64 v[4:5], v[4:5], 2, s[6:7]
	global_load_dword v4, v[4:5], off nt
	v_add_u32_e32 v7, 0x1c00, v0
	s_waitcnt vmcnt(0)
	v_mul_f32_e32 v6, v60, v4
	v_or_b32_e32 v4, s8, v43
	v_ashrrev_i32_e32 v5, 31, v4
	v_lshl_add_u64 v[4:5], v[4:5], 2, s[6:7]
	global_load_dword v4, v[4:5], off nt
	s_waitcnt vmcnt(0)
	v_mul_f32_e32 v4, v48, v4
	ds_write2_b32 v7, v6, v4 offset0:56 offset1:122
	v_or_b32_e32 v4, s8, v44
	v_ashrrev_i32_e32 v5, 31, v4
	v_lshl_add_u64 v[4:5], v[4:5], 2, s[6:7]
	global_load_dword v4, v[4:5], off nt
	s_waitcnt vmcnt(0)
	v_mul_f32_e32 v6, v53, v4
	v_or_b32_e32 v4, s8, v45
	v_ashrrev_i32_e32 v5, 31, v4
	v_lshl_add_u64 v[4:5], v[4:5], 2, s[6:7]
	global_load_dword v4, v[4:5], off nt
	s_waitcnt vmcnt(0)
	v_mul_f32_e32 v4, v47, v4
	ds_write2_b32 v7, v6, v4 offset0:188 offset1:254
	s_waitcnt lgkmcnt(0)
	ds_read2_b32 v[6:7], v46 offset0:33 offset1:41
	ds_read2_b32 v[52:53], v46 offset1:8
	ds_read2_b32 v[54:55], v46 offset0:66 offset1:74
	ds_read2_b32 v[56:57], v46 offset0:99 offset1:107
	v_lshl_add_u64 v[4:5], s[8:9], 1, v[2:3]
	s_mov_b32 s8, 0xffff0000
	s_waitcnt lgkmcnt(3)
	v_bfe_u32 v48, v6, 16, 1
	s_waitcnt lgkmcnt(2)
	v_bfe_u32 v47, v52, 16, 1
	v_add3_u32 v47, v52, v47, s33
	v_lshrrev_b32_e32 v47, 16, v47
	v_add3_u32 v6, v6, v48, s33
	ds_read2_b32 v[58:59], v46 offset0:132 offset1:140
	ds_read2_b32 v[60:61], v46 offset0:165 offset1:173
	v_and_or_b32 v48, v6, s8, v47
	s_waitcnt lgkmcnt(3)
	v_bfe_u32 v6, v54, 16, 1
	v_add3_u32 v6, v54, v6, s33
	s_waitcnt lgkmcnt(2)
	v_bfe_u32 v47, v56, 16, 1
	v_lshrrev_b32_e32 v6, 16, v6
	v_add3_u32 v47, v56, v47, s33
	ds_read2_b32 v[62:63], v46 offset0:198 offset1:206
	ds_read2_b32 v[64:65], v46 offset0:231 offset1:239
	v_and_or_b32 v49, v47, s8, v6
	s_waitcnt lgkmcnt(3)
	v_bfe_u32 v6, v58, 16, 1
	v_add3_u32 v6, v58, v6, s33
	s_waitcnt lgkmcnt(2)
	v_bfe_u32 v47, v60, 16, 1
	v_lshrrev_b32_e32 v6, 16, v6
	v_add3_u32 v47, v60, v47, s33
	v_and_or_b32 v50, v47, s8, v6
	s_waitcnt lgkmcnt(1)
	v_bfe_u32 v6, v62, 16, 1
	v_add3_u32 v6, v62, v6, s33
	s_waitcnt lgkmcnt(0)
	v_bfe_u32 v47, v64, 16, 1
	v_lshrrev_b32_e32 v6, 16, v6
	v_add3_u32 v47, v64, v47, s33
	v_and_or_b32 v51, v47, s8, v6
	v_bfe_u32 v6, v53, 16, 1
	v_add3_u32 v6, v53, v6, s33
	v_bfe_u32 v47, v7, 16, 1
	v_lshl_add_u64 v[68:69], v[4:5], 0, v[68:69]
	v_lshrrev_b32_e32 v6, 16, v6
	v_add3_u32 v7, v7, v47, s33
	global_store_dwordx4 v[68:69], v[48:51], off
	v_add_u32_e32 v68, 16, v66
	v_ashrrev_i32_e32 v69, 31, v68
	v_and_or_b32 v48, v7, s8, v6
	v_bfe_u32 v6, v55, 16, 1
	v_add3_u32 v6, v55, v6, s33
	v_bfe_u32 v7, v57, 16, 1
	v_lshrrev_b32_e32 v6, 16, v6
	v_add3_u32 v7, v57, v7, s33
	v_and_or_b32 v49, v7, s8, v6
	v_bfe_u32 v6, v59, 16, 1
	v_add3_u32 v6, v59, v6, s33
	v_bfe_u32 v7, v61, 16, 1
	v_lshrrev_b32_e32 v6, 16, v6
	v_add3_u32 v7, v61, v7, s33
	v_and_or_b32 v50, v7, s8, v6
	v_bfe_u32 v6, v63, 16, 1
	v_add3_u32 v6, v63, v6, s33
	v_bfe_u32 v7, v65, 16, 1
	v_lshrrev_b32_e32 v6, 16, v6
	v_add3_u32 v7, v65, v7, s33
	v_and_or_b32 v51, v7, s8, v6
	v_add_u32_e32 v6, 8, v66
	v_ashrrev_i32_e32 v7, 31, v6
	v_lshlrev_b64 v[6:7], 11, v[6:7]
	v_lshl_add_u64 v[6:7], v[4:5], 0, v[6:7]
	global_store_dwordx4 v[6:7], v[48:51], off
	ds_read2_b32 v[6:7], v46 offset0:49 offset1:57
	ds_read2_b32 v[52:53], v46 offset0:16 offset1:24
	ds_read2_b32 v[54:55], v46 offset0:82 offset1:90
	ds_read2_b32 v[56:57], v46 offset0:115 offset1:123
	ds_read2_b32 v[58:59], v46 offset0:148 offset1:156
	ds_read2_b32 v[60:61], v46 offset0:181 offset1:189
	ds_read2_b32 v[62:63], v46 offset0:214 offset1:222
	ds_read2_b32 v[64:65], v46 offset0:247 offset1:255
	s_waitcnt lgkmcnt(7)
	v_bfe_u32 v48, v6, 16, 1
	s_waitcnt lgkmcnt(6)
	v_bfe_u32 v47, v52, 16, 1
	v_add3_u32 v47, v52, v47, s33
	v_lshrrev_b32_e32 v47, 16, v47
	v_add3_u32 v6, v6, v48, s33
	v_and_or_b32 v48, v6, s8, v47
	s_waitcnt lgkmcnt(5)
	v_bfe_u32 v6, v54, 16, 1
	v_add3_u32 v6, v54, v6, s33
	s_waitcnt lgkmcnt(4)
	v_bfe_u32 v47, v56, 16, 1
	v_lshrrev_b32_e32 v6, 16, v6
	v_add3_u32 v47, v56, v47, s33
	v_and_or_b32 v49, v47, s8, v6
	s_waitcnt lgkmcnt(3)
	v_bfe_u32 v6, v58, 16, 1
	v_add3_u32 v6, v58, v6, s33
	s_waitcnt lgkmcnt(2)
	v_bfe_u32 v47, v60, 16, 1
	v_lshrrev_b32_e32 v6, 16, v6
	v_add3_u32 v47, v60, v47, s33
	v_and_or_b32 v50, v47, s8, v6
	s_waitcnt lgkmcnt(1)
	v_bfe_u32 v6, v62, 16, 1
	v_add3_u32 v6, v62, v6, s33
	s_waitcnt lgkmcnt(0)
	v_bfe_u32 v47, v64, 16, 1
	v_lshrrev_b32_e32 v6, 16, v6
	v_add3_u32 v47, v64, v47, s33
	v_and_or_b32 v51, v47, s8, v6
	v_bfe_u32 v6, v53, 16, 1
	v_lshlrev_b64 v[68:69], 11, v[68:69]
	v_add3_u32 v6, v53, v6, s33
	v_bfe_u32 v47, v7, 16, 1
	v_lshl_add_u64 v[68:69], v[4:5], 0, v[68:69]
	v_lshrrev_b32_e32 v6, 16, v6
	v_add3_u32 v7, v7, v47, s33
	global_store_dwordx4 v[68:69], v[48:51], off
	s_nop 1
	v_and_or_b32 v48, v7, s8, v6
	v_bfe_u32 v6, v55, 16, 1
	v_add3_u32 v6, v55, v6, s33
	v_bfe_u32 v7, v57, 16, 1
	v_lshrrev_b32_e32 v6, 16, v6
	v_add3_u32 v7, v57, v7, s33
	v_and_or_b32 v49, v7, s8, v6
	v_bfe_u32 v6, v59, 16, 1
	v_add3_u32 v6, v59, v6, s33
	v_bfe_u32 v7, v61, 16, 1
	v_lshrrev_b32_e32 v6, 16, v6
	v_add3_u32 v7, v61, v7, s33
	v_and_or_b32 v50, v7, s8, v6
	v_bfe_u32 v6, v63, 16, 1
	v_add3_u32 v6, v63, v6, s33
	v_bfe_u32 v7, v65, 16, 1
	v_lshrrev_b32_e32 v6, 16, v6
	v_add3_u32 v7, v65, v7, s33
	v_and_or_b32 v51, v7, s8, v6
	v_add_u32_e32 v6, 24, v66
	v_ashrrev_i32_e32 v7, 31, v6
	v_lshlrev_b64 v[6:7], 11, v[6:7]
	v_lshl_add_u64 v[4:5], v[4:5], 0, v[6:7]
	global_store_dwordx4 v[4:5], v[48:51], off
	s_waitcnt lgkmcnt(0)
	s_cbranch_scc0 .LBB0_1954
; __device__ __forceinline__ void conv_weight(const float* W, int ldw, int K, int Nphys, int Nvalid, int mode, const float* g, bf16_t* WT, LAS float* scr, int gw, int NGW, int lane, int& rot) {
;     ...
;         const int kb = it / nblk, nb = it % nblk, k0 = 64 * kb, n0 = 32 * nb;
;         const int prow = n0 + (lane & 31); const bool ok = prow < Nvalid; const int col = ok ? colmap(mode, prow) : 0;
;         float wv_[32];
; #pragma unroll
;         for (int i = 0; i < 32; ++i) { const int kk = 2 * i + (lane >> 5); wv_[i] = ok ? W[(size_t)(k0 + kk) * ldw + col] : 0.f; }
.LBB0_1890:
	s_ashr_i32 s3, s0, 31
	s_lshr_b32 s3, s3, 29
	s_add_i32 s3, s0, s3
	s_ashr_i32 s3, s3, 3
	s_lshl_b32 s8, s3, 6
	s_lshl_b32 s3, s3, 8
	s_sub_i32 s9, s1, s3
	v_add_u32_e32 v4, s9, v8
	s_movk_i32 s9, 0x100
	v_cmp_gt_i32_e32 vcc, s9, v4
	s_waitcnt vmcnt(7)
	v_mov_b32_e32 v68, 0
	s_waitcnt vmcnt(5)
	v_mov_b32_e32 v75, 0
	v_cndmask_b32_e32 v4, 0, v4, vcc
	v_ashrrev_i32_e32 v5, 31, v4
	v_lshl_add_u64 v[6:7], v[4:5], 2, s[4:5]
	v_or_b32_e32 v4, s8, v9
	v_ashrrev_i32_e32 v5, 31, v4
	s_and_saveexec_b64 s[10:11], vcc
	s_cbranch_execz .LBB0_1892
	v_lshlrev_b64 v[48:49], 10, v[4:5]
	v_lshl_add_u64 v[48:49], v[6:7], 0, v[48:49]
	global_load_dword v75, v[48:49], off nt
.LBB0_1892:
	s_or_b64 exec, exec, s[10:11]
	s_and_saveexec_b64 s[10:11], vcc
	s_cbranch_execz .LBB0_1894
	v_or_b32_e32 v48, 2, v4
	v_ashrrev_i32_e32 v49, 31, v48
	v_lshlrev_b64 v[48:49], 10, v[48:49]
	v_lshl_add_u64 v[48:49], v[6:7], 0, v[48:49]
	global_load_dword v68, v[48:49], off nt
.LBB0_1894:
	s_or_b64 exec, exec, s[10:11]
	v_mov_b32_e32 v69, 0
	v_mov_b32_e32 v76, 0
	s_and_saveexec_b64 s[10:11], vcc
	s_cbranch_execz .LBB0_1896
	v_or_b32_e32 v48, 4, v4
	v_ashrrev_i32_e32 v49, 31, v48
	v_lshlrev_b64 v[48:49], 10, v[48:49]
	v_lshl_add_u64 v[48:49], v[6:7], 0, v[48:49]
	global_load_dword v76, v[48:49], off nt
.LBB0_1896:
	s_or_b64 exec, exec, s[10:11]
	s_and_saveexec_b64 s[10:11], vcc
	s_cbranch_execz .LBB0_1898
	v_or_b32_e32 v48, 6, v4
	v_ashrrev_i32_e32 v49, 31, v48
	v_lshlrev_b64 v[48:49], 10, v[48:49]
	v_lshl_add_u64 v[48:49], v[6:7], 0, v[48:49]
	global_load_dword v69, v[48:49], off nt
.LBB0_1898:
	s_or_b64 exec, exec, s[10:11]
	s_waitcnt vmcnt(4)
	v_mov_b32_e32 v71, 0
	v_mov_b32_e32 v78, 0
	s_and_saveexec_b64 s[10:11], vcc
	s_cbranch_execz .LBB0_1900
	v_or_b32_e32 v48, 8, v4
	v_ashrrev_i32_e32 v49, 31, v48
	v_lshlrev_b64 v[48:49], 10, v[48:49]
	v_lshl_add_u64 v[48:49], v[6:7], 0, v[48:49]
	global_load_dword v78, v[48:49], off nt
.LBB0_1900:
	s_or_b64 exec, exec, s[10:11]
	s_and_saveexec_b64 s[10:11], vcc
	s_cbranch_execz .LBB0_1902
	v_or_b32_e32 v48, 10, v4
	v_ashrrev_i32_e32 v49, 31, v48
	v_lshlrev_b64 v[48:49], 10, v[48:49]
	v_lshl_add_u64 v[48:49], v[6:7], 0, v[48:49]
	global_load_dword v71, v[48:49], off nt
.LBB0_1902:
	s_or_b64 exec, exec, s[10:11]
	v_mov_b32_e32 v59, 0
	v_mov_b32_e32 v77, 0
	s_and_saveexec_b64 s[10:11], vcc
	s_cbranch_execz .LBB0_1904
	v_or_b32_e32 v48, 12, v4
	v_ashrrev_i32_e32 v49, 31, v48
	v_lshlrev_b64 v[48:49], 10, v[48:49]
	v_lshl_add_u64 v[48:49], v[6:7], 0, v[48:49]
	global_load_dword v77, v[48:49], off nt
.LBB0_1904:
	s_or_b64 exec, exec, s[10:11]
	s_and_saveexec_b64 s[10:11], vcc
	s_cbranch_execz .LBB0_1906
	v_or_b32_e32 v48, 14, v4
	v_ashrrev_i32_e32 v49, 31, v48
	v_lshlrev_b64 v[48:49], 10, v[48:49]
	v_lshl_add_u64 v[48:49], v[6:7], 0, v[48:49]
	global_load_dword v59, v[48:49], off nt
.LBB0_1906:
	s_or_b64 exec, exec, s[10:11]
	v_mov_b32_e32 v62, 0
	v_mov_b32_e32 v72, 0
	s_and_saveexec_b64 s[10:11], vcc
	s_cbranch_execz .LBB0_1908
	v_or_b32_e32 v48, 16, v4
	v_ashrrev_i32_e32 v49, 31, v48
	v_lshlrev_b64 v[48:49], 10, v[48:49]
	v_lshl_add_u64 v[48:49], v[6:7], 0, v[48:49]
	global_load_dword v72, v[48:49], off nt
.LBB0_1908:
	s_or_b64 exec, exec, s[10:11]
	s_and_saveexec_b64 s[10:11], vcc
	s_cbranch_execz .LBB0_1910
	v_or_b32_e32 v48, 18, v4
	v_ashrrev_i32_e32 v49, 31, v48
	v_lshlrev_b64 v[48:49], 10, v[48:49]
	v_lshl_add_u64 v[48:49], v[6:7], 0, v[48:49]
	global_load_dword v62, v[48:49], off nt
.LBB0_1910:
	s_or_b64 exec, exec, s[10:11]
	v_mov_b32_e32 v61, 0
	v_mov_b32_e32 v70, 0
	s_and_saveexec_b64 s[10:11], vcc
	s_cbranch_execz .LBB0_1912
	v_or_b32_e32 v48, 20, v4
	v_ashrrev_i32_e32 v49, 31, v48
	v_lshlrev_b64 v[48:49], 10, v[48:49]
	v_lshl_add_u64 v[48:49], v[6:7], 0, v[48:49]
	global_load_dword v70, v[48:49], off nt
.LBB0_1912:
	s_or_b64 exec, exec, s[10:11]
	s_and_saveexec_b64 s[10:11], vcc
	s_cbranch_execz .LBB0_1914
	v_or_b32_e32 v48, 22, v4
	v_ashrrev_i32_e32 v49, 31, v48
	v_lshlrev_b64 v[48:49], 10, v[48:49]
	v_lshl_add_u64 v[48:49], v[6:7], 0, v[48:49]
	global_load_dword v61, v[48:49], off nt
.LBB0_1914:
	s_or_b64 exec, exec, s[10:11]
	v_mov_b32_e32 v64, 0
	v_mov_b32_e32 v74, 0
	s_and_saveexec_b64 s[10:11], vcc
	s_cbranch_execz .LBB0_1916
	v_or_b32_e32 v48, 24, v4
	v_ashrrev_i32_e32 v49, 31, v48
	v_lshlrev_b64 v[48:49], 10, v[48:49]
	v_lshl_add_u64 v[48:49], v[6:7], 0, v[48:49]
	global_load_dword v74, v[48:49], off nt
.LBB0_1916:
	s_or_b64 exec, exec, s[10:11]
	s_and_saveexec_b64 s[10:11], vcc
	s_cbranch_execz .LBB0_1918
	v_or_b32_e32 v48, 26, v4
	v_ashrrev_i32_e32 v49, 31, v48
	v_lshlrev_b64 v[48:49], 10, v[48:49]
	v_lshl_add_u64 v[48:49], v[6:7], 0, v[48:49]
	global_load_dword v64, v[48:49], off nt
.LBB0_1918:
	s_or_b64 exec, exec, s[10:11]
	v_mov_b32_e32 v52, 0
	v_mov_b32_e32 v73, 0
	s_and_saveexec_b64 s[10:11], vcc
	s_cbranch_execz .LBB0_1920
	v_or_b32_e32 v48, 28, v4
	v_ashrrev_i32_e32 v49, 31, v48
	v_lshlrev_b64 v[48:49], 10, v[48:49]
	v_lshl_add_u64 v[48:49], v[6:7], 0, v[48:49]
	global_load_dword v73, v[48:49], off nt
; __device__ __forceinline__ void conv_weight(const float* W, int ldw, int K, int Nphys, int Nvalid, int mode, const float* g, bf16_t* WT, LAS float* scr, int gw, int NGW, int lane, int& rot) {
;     ...
;         for (int i = 0; i < 32; ++i) { const int kk = 2 * i + (lane >> 5); wv_[i] = ok ? W[(size_t)(k0 + kk) * ldw + col] : 0.f; }
.LBB0_1920:
	s_or_b64 exec, exec, s[10:11]
	s_and_saveexec_b64 s[10:11], vcc
	s_cbranch_execz .LBB0_1922
	v_or_b32_e32 v48, 30, v4
	v_ashrrev_i32_e32 v49, 31, v48
	v_lshlrev_b64 v[48:49], 10, v[48:49]
	v_lshl_add_u64 v[48:49], v[6:7], 0, v[48:49]
	global_load_dword v52, v[48:49], off nt
.LBB0_1922:
	s_or_b64 exec, exec, s[10:11]
	v_mov_b32_e32 v55, 0
	v_mov_b32_e32 v65, 0
	s_and_saveexec_b64 s[10:11], vcc
	s_cbranch_execz .LBB0_1924
	v_or_b32_e32 v48, 32, v4
	v_ashrrev_i32_e32 v49, 31, v48
	v_lshlrev_b64 v[48:49], 10, v[48:49]
	v_lshl_add_u64 v[48:49], v[6:7], 0, v[48:49]
	global_load_dword v65, v[48:49], off nt
.LBB0_1924:
	s_or_b64 exec, exec, s[10:11]
	s_and_saveexec_b64 s[10:11], vcc
	s_cbranch_execz .LBB0_1926
	v_or_b32_e32 v48, 34, v4
	v_ashrrev_i32_e32 v49, 31, v48
	v_lshlrev_b64 v[48:49], 10, v[48:49]
	v_lshl_add_u64 v[48:49], v[6:7], 0, v[48:49]
	global_load_dword v55, v[48:49], off nt
.LBB0_1926:
	s_or_b64 exec, exec, s[10:11]
	v_mov_b32_e32 v54, 0
	v_mov_b32_e32 v63, 0
	s_and_saveexec_b64 s[10:11], vcc
	s_cbranch_execz .LBB0_1928
	v_or_b32_e32 v48, 36, v4
	v_ashrrev_i32_e32 v49, 31, v48
	v_lshlrev_b64 v[48:49], 10, v[48:49]
	v_lshl_add_u64 v[48:49], v[6:7], 0, v[48:49]
	global_load_dword v63, v[48:49], off nt
.LBB0_1928:
	s_or_b64 exec, exec, s[10:11]
	s_and_saveexec_b64 s[10:11], vcc
	s_cbranch_execz .LBB0_1930
	v_or_b32_e32 v48, 38, v4
	v_ashrrev_i32_e32 v49, 31, v48
	v_lshlrev_b64 v[48:49], 10, v[48:49]
	v_lshl_add_u64 v[48:49], v[6:7], 0, v[48:49]
	global_load_dword v54, v[48:49], off nt
.LBB0_1930:
	s_or_b64 exec, exec, s[10:11]
	v_mov_b32_e32 v57, 0
	v_mov_b32_e32 v67, 0
	s_and_saveexec_b64 s[10:11], vcc
	s_cbranch_execz .LBB0_1932
	v_or_b32_e32 v48, 40, v4
	v_ashrrev_i32_e32 v49, 31, v48
	v_lshlrev_b64 v[48:49], 10, v[48:49]
	v_lshl_add_u64 v[48:49], v[6:7], 0, v[48:49]
	global_load_dword v67, v[48:49], off nt
.LBB0_1932:
	s_or_b64 exec, exec, s[10:11]
	s_and_saveexec_b64 s[10:11], vcc
	s_cbranch_execz .LBB0_1934
	v_or_b32_e32 v48, 42, v4
	v_ashrrev_i32_e32 v49, 31, v48
	v_lshlrev_b64 v[48:49], 10, v[48:49]
	v_lshl_add_u64 v[48:49], v[6:7], 0, v[48:49]
	global_load_dword v57, v[48:49], off nt
.LBB0_1934:
	s_or_b64 exec, exec, s[10:11]
	v_mov_b32_e32 v49, 0
	v_mov_b32_e32 v66, 0
	s_and_saveexec_b64 s[10:11], vcc
	s_cbranch_execz .LBB0_1936
	v_or_b32_e32 v50, 44, v4
	v_ashrrev_i32_e32 v51, 31, v50
	v_lshlrev_b64 v[50:51], 10, v[50:51]
	v_lshl_add_u64 v[50:51], v[6:7], 0, v[50:51]
	global_load_dword v66, v[50:51], off nt
.LBB0_1936:
	s_or_b64 exec, exec, s[10:11]
	s_and_saveexec_b64 s[10:11], vcc
	s_cbranch_execz .LBB0_1938
	v_or_b32_e32 v48, 46, v4
	v_ashrrev_i32_e32 v49, 31, v48
	v_lshlrev_b64 v[48:49], 10, v[48:49]
	v_lshl_add_u64 v[48:49], v[6:7], 0, v[48:49]
	global_load_dword v49, v[48:49], off nt
.LBB0_1938:
	s_or_b64 exec, exec, s[10:11]
	v_mov_b32_e32 v51, 0
	v_mov_b32_e32 v58, 0
	s_and_saveexec_b64 s[10:11], vcc
	s_cbranch_execz .LBB0_1940
	v_or_b32_e32 v80, 48, v4
	v_ashrrev_i32_e32 v81, 31, v80
	v_lshlrev_b64 v[80:81], 10, v[80:81]
	v_lshl_add_u64 v[80:81], v[6:7], 0, v[80:81]
	global_load_dword v58, v[80:81], off nt
.LBB0_1940:
	s_or_b64 exec, exec, s[10:11]
	s_and_saveexec_b64 s[10:11], vcc
	s_cbranch_execz .LBB0_1942
	v_or_b32_e32 v50, 50, v4
	v_ashrrev_i32_e32 v51, 31, v50
	v_lshlrev_b64 v[50:51], 10, v[50:51]
	v_lshl_add_u64 v[50:51], v[6:7], 0, v[50:51]
	global_load_dword v51, v[50:51], off nt
.LBB0_1942:
	s_or_b64 exec, exec, s[10:11]
	v_mov_b32_e32 v50, 0
	v_mov_b32_e32 v56, 0
	s_and_saveexec_b64 s[10:11], vcc
	s_cbranch_execz .LBB0_1944
	v_or_b32_e32 v80, 52, v4
	v_ashrrev_i32_e32 v81, 31, v80
	v_lshlrev_b64 v[80:81], 10, v[80:81]
	v_lshl_add_u64 v[80:81], v[6:7], 0, v[80:81]
	global_load_dword v56, v[80:81], off nt
.LBB0_1944:
	s_or_b64 exec, exec, s[10:11]
	s_and_saveexec_b64 s[10:11], vcc
	s_cbranch_execz .LBB0_1946
	v_or_b32_e32 v80, 54, v4
	v_ashrrev_i32_e32 v81, 31, v80
	v_lshlrev_b64 v[80:81], 10, v[80:81]
	v_lshl_add_u64 v[80:81], v[6:7], 0, v[80:81]
	global_load_dword v50, v[80:81], off nt
.LBB0_1946:
	s_or_b64 exec, exec, s[10:11]
	v_mov_b32_e32 v48, 0
	v_mov_b32_e32 v60, 0
	s_and_saveexec_b64 s[10:11], vcc
	s_cbranch_execz .LBB0_1948
	v_or_b32_e32 v80, 56, v4
	v_ashrrev_i32_e32 v81, 31, v80
	v_lshlrev_b64 v[80:81], 10, v[80:81]
	v_lshl_add_u64 v[80:81], v[6:7], 0, v[80:81]
	global_load_dword v60, v[80:81], off nt
.LBB0_1948:
	s_or_b64 exec, exec, s[10:11]
	s_and_saveexec_b64 s[10:11], vcc
	s_cbranch_execz .LBB0_1950
	v_or_b32_e32 v80, 58, v4
	v_ashrrev_i32_e32 v81, 31, v80
	v_lshlrev_b64 v[80:81], 10, v[80:81]
	v_lshl_add_u64 v[80:81], v[6:7], 0, v[80:81]
	global_load_dword v48, v[80:81], off nt
.LBB0_1950:
	s_or_b64 exec, exec, s[10:11]
	v_mov_b32_e32 v47, 0
	v_mov_b32_e32 v53, 0
	s_and_saveexec_b64 s[10:11], vcc
	s_cbranch_execz .LBB0_1952
	v_or_b32_e32 v80, 60, v4
	v_ashrrev_i32_e32 v81, 31, v80
	v_lshlrev_b64 v[80:81], 10, v[80:81]
	v_lshl_add_u64 v[80:81], v[6:7], 0, v[80:81]
	global_load_dword v53, v[80:81], off nt
.LBB0_1952:
	s_or_b64 exec, exec, s[10:11]
	s_and_saveexec_b64 s[10:11], vcc
	s_cbranch_execz .LBB0_1889
	v_or_b32_e32 v80, 62, v4
	v_ashrrev_i32_e32 v81, 31, v80
	v_lshlrev_b64 v[80:81], 10, v[80:81]
	v_lshl_add_u64 v[6:7], v[6:7], 0, v[80:81]
	global_load_dword v47, v[6:7], off nt
	s_branch .LBB0_1889

; __device__ __forceinline__ void conv_weight(const float* W, int ldw, int K, int Nphys, int Nvalid, int mode, const float* g, bf16_t* WT, LAS float* scr, int gw, int NGW, int lane, int& rot) {
;     ...
;         const int kb = it / nblk, nb = it % nblk, k0 = 64 * kb, n0 = 32 * nb;
;         const int prow = n0 + (lane & 31); const bool ok = prow < Nvalid; const int col = ok ? colmap(mode, prow) : 0;
;         float wv_[32];
; #pragma unroll
;         for (int i = 0; i < 32; ++i) { const int kk = 2 * i + (lane >> 5); wv_[i] = ok ? W[(size_t)(k0 + kk) * ldw + col] : 0.f; }
.LBB0_1957:
	s_ashr_i32 s3, s0, 31
	s_lshr_b32 s3, s3, 27
	s_add_i32 s3, s0, s3
	s_ashr_i32 s3, s3, 5
	s_lshl_b32 s6, s3, 6
	s_lshl_b32 s3, s3, 10
	s_sub_i32 s7, s1, s3
	v_add_u32_e32 v4, s7, v8
	s_movk_i32 s7, 0x400
	v_cmp_gt_i32_e32 vcc, s7, v4
	v_or_b32_e32 v6, s6, v9
	v_mov_b32_e32 v12, 0
	v_cndmask_b32_e32 v4, 0, v4, vcc
	v_ashrrev_i32_e32 v5, 31, v4
	v_lshl_add_u64 v[4:5], v[4:5], 2, s[4:5]
	v_mov_b32_e32 v7, 0
	s_and_saveexec_b64 s[8:9], vcc
	s_cbranch_execz .LBB0_1959
	v_ashrrev_i32_e32 v7, 31, v6
	v_lshlrev_b64 v[14:15], 12, v[6:7]
	v_lshl_add_u64 v[14:15], v[4:5], 0, v[14:15]
	global_load_dword v7, v[14:15], off nt
.LBB0_1959:
	s_or_b64 exec, exec, s[8:9]
	s_and_saveexec_b64 s[8:9], vcc
	s_cbranch_execz .LBB0_1961
	v_or_b32_e32 v12, 2, v6
	v_ashrrev_i32_e32 v13, 31, v12
	v_lshlrev_b64 v[12:13], 12, v[12:13]
	v_lshl_add_u64 v[12:13], v[4:5], 0, v[12:13]
	global_load_dword v12, v[12:13], off nt
.LBB0_1961:
	s_or_b64 exec, exec, s[8:9]
	v_mov_b32_e32 v13, 0
	v_mov_b32_e32 v14, 0
	s_and_saveexec_b64 s[8:9], vcc
	s_cbranch_execz .LBB0_1963
	v_or_b32_e32 v14, 4, v6
	v_ashrrev_i32_e32 v15, 31, v14
	v_lshlrev_b64 v[14:15], 12, v[14:15]
	v_lshl_add_u64 v[14:15], v[4:5], 0, v[14:15]
	global_load_dword v14, v[14:15], off nt
.LBB0_1963:
	s_or_b64 exec, exec, s[8:9]
	s_and_saveexec_b64 s[8:9], vcc
	s_cbranch_execz .LBB0_1965
	v_or_b32_e32 v16, 6, v6
	v_ashrrev_i32_e32 v17, 31, v16
	v_lshlrev_b64 v[16:17], 12, v[16:17]
	v_lshl_add_u64 v[16:17], v[4:5], 0, v[16:17]
	global_load_dword v13, v[16:17], off nt
.LBB0_1965:
	s_or_b64 exec, exec, s[8:9]
	v_mov_b32_e32 v15, 0
	v_mov_b32_e32 v16, 0
	s_and_saveexec_b64 s[8:9], vcc
	s_cbranch_execz .LBB0_1967
	v_or_b32_e32 v16, 8, v6
	v_ashrrev_i32_e32 v17, 31, v16
	v_lshlrev_b64 v[16:17], 12, v[16:17]
	v_lshl_add_u64 v[16:17], v[4:5], 0, v[16:17]
	global_load_dword v16, v[16:17], off nt
.LBB0_1967:
	s_or_b64 exec, exec, s[8:9]
	s_and_saveexec_b64 s[8:9], vcc
	s_cbranch_execz .LBB0_1969
	v_or_b32_e32 v18, 10, v6
	v_ashrrev_i32_e32 v19, 31, v18
	v_lshlrev_b64 v[18:19], 12, v[18:19]
	v_lshl_add_u64 v[18:19], v[4:5], 0, v[18:19]
	global_load_dword v15, v[18:19], off nt
.LBB0_1969:
	s_or_b64 exec, exec, s[8:9]
	v_mov_b32_e32 v17, 0
	v_mov_b32_e32 v18, 0
	s_and_saveexec_b64 s[8:9], vcc
	s_cbranch_execz .LBB0_1971
	v_or_b32_e32 v18, 12, v6
	v_ashrrev_i32_e32 v19, 31, v18
	v_lshlrev_b64 v[18:19], 12, v[18:19]
	v_lshl_add_u64 v[18:19], v[4:5], 0, v[18:19]
	global_load_dword v18, v[18:19], off nt
.LBB0_1971:
	s_or_b64 exec, exec, s[8:9]
	s_and_saveexec_b64 s[8:9], vcc
	s_cbranch_execz .LBB0_1973
	v_or_b32_e32 v20, 14, v6
	v_ashrrev_i32_e32 v21, 31, v20
	v_lshlrev_b64 v[20:21], 12, v[20:21]
	v_lshl_add_u64 v[20:21], v[4:5], 0, v[20:21]
	global_load_dword v17, v[20:21], off nt
.LBB0_1973:
	s_or_b64 exec, exec, s[8:9]
	v_mov_b32_e32 v19, 0
	v_mov_b32_e32 v20, 0
	s_and_saveexec_b64 s[8:9], vcc
	s_cbranch_execz .LBB0_1975
	v_or_b32_e32 v20, 16, v6
	v_ashrrev_i32_e32 v21, 31, v20
	v_lshlrev_b64 v[20:21], 12, v[20:21]
	v_lshl_add_u64 v[20:21], v[4:5], 0, v[20:21]
	global_load_dword v20, v[20:21], off nt
.LBB0_1975:
	s_or_b64 exec, exec, s[8:9]
	s_and_saveexec_b64 s[8:9], vcc
	s_cbranch_execz .LBB0_1977
	v_or_b32_e32 v22, 18, v6
	v_ashrrev_i32_e32 v23, 31, v22
	v_lshlrev_b64 v[22:23], 12, v[22:23]
	v_lshl_add_u64 v[22:23], v[4:5], 0, v[22:23]
	global_load_dword v19, v[22:23], off nt
.LBB0_1977:
	s_or_b64 exec, exec, s[8:9]
	v_mov_b32_e32 v21, 0
	v_mov_b32_e32 v22, 0
	s_and_saveexec_b64 s[8:9], vcc
	s_cbranch_execz .LBB0_1979
	v_or_b32_e32 v22, 20, v6
	v_ashrrev_i32_e32 v23, 31, v22
	v_lshlrev_b64 v[22:23], 12, v[22:23]
	v_lshl_add_u64 v[22:23], v[4:5], 0, v[22:23]
	global_load_dword v22, v[22:23], off nt
.LBB0_1979:
	s_or_b64 exec, exec, s[8:9]
	s_and_saveexec_b64 s[8:9], vcc
	s_cbranch_execz .LBB0_1981
	v_or_b32_e32 v24, 22, v6
	v_ashrrev_i32_e32 v25, 31, v24
	v_lshlrev_b64 v[24:25], 12, v[24:25]
	v_lshl_add_u64 v[24:25], v[4:5], 0, v[24:25]
	global_load_dword v21, v[24:25], off nt
.LBB0_1981:
	s_or_b64 exec, exec, s[8:9]
	v_mov_b32_e32 v23, 0
	v_mov_b32_e32 v24, 0
	s_and_saveexec_b64 s[8:9], vcc
	s_cbranch_execz .LBB0_1983
	v_or_b32_e32 v24, 24, v6
	v_ashrrev_i32_e32 v25, 31, v24
	v_lshlrev_b64 v[24:25], 12, v[24:25]
	v_lshl_add_u64 v[24:25], v[4:5], 0, v[24:25]
	global_load_dword v24, v[24:25], off nt
.LBB0_1983:
	s_or_b64 exec, exec, s[8:9]
	s_and_saveexec_b64 s[8:9], vcc
	s_cbranch_execz .LBB0_1985
	v_or_b32_e32 v26, 26, v6
	v_ashrrev_i32_e32 v27, 31, v26
	v_lshlrev_b64 v[26:27], 12, v[26:27]
	v_lshl_add_u64 v[26:27], v[4:5], 0, v[26:27]
	global_load_dword v23, v[26:27], off nt
.LBB0_1985:
	s_or_b64 exec, exec, s[8:9]
	v_mov_b32_e32 v25, 0
	v_mov_b32_e32 v26, 0
	s_and_saveexec_b64 s[8:9], vcc
	s_cbranch_execz .LBB0_1987
	v_or_b32_e32 v26, 28, v6
	v_ashrrev_i32_e32 v27, 31, v26
	v_lshlrev_b64 v[26:27], 12, v[26:27]
	v_lshl_add_u64 v[26:27], v[4:5], 0, v[26:27]
	global_load_dword v26, v[26:27], off nt
; __device__ __forceinline__ void conv_weight(const float* W, int ldw, int K, int Nphys, int Nvalid, int mode, const float* g, bf16_t* WT, LAS float* scr, int gw, int NGW, int lane, int& rot) {
;     ...
;         for (int i = 0; i < 32; ++i) { const int kk = 2 * i + (lane >> 5); wv_[i] = ok ? W[(size_t)(k0 + kk) * ldw + col] : 0.f; }
.LBB0_1987:
	s_or_b64 exec, exec, s[8:9]
	s_and_saveexec_b64 s[8:9], vcc
	s_cbranch_execz .LBB0_1989
	v_or_b32_e32 v28, 30, v6
	v_ashrrev_i32_e32 v29, 31, v28
	v_lshlrev_b64 v[28:29], 12, v[28:29]
	v_lshl_add_u64 v[28:29], v[4:5], 0, v[28:29]
	global_load_dword v25, v[28:29], off nt
.LBB0_1989:
	s_or_b64 exec, exec, s[8:9]
	v_mov_b32_e32 v27, 0
	v_mov_b32_e32 v28, 0
	s_and_saveexec_b64 s[8:9], vcc
	s_cbranch_execz .LBB0_1991
	v_or_b32_e32 v28, 32, v6
	v_ashrrev_i32_e32 v29, 31, v28
	v_lshlrev_b64 v[28:29], 12, v[28:29]
	v_lshl_add_u64 v[28:29], v[4:5], 0, v[28:29]
	global_load_dword v28, v[28:29], off nt
.LBB0_1991:
	s_or_b64 exec, exec, s[8:9]
	s_and_saveexec_b64 s[8:9], vcc
	s_cbranch_execz .LBB0_1993
	v_or_b32_e32 v30, 34, v6
	v_ashrrev_i32_e32 v31, 31, v30
	v_lshlrev_b64 v[30:31], 12, v[30:31]
	v_lshl_add_u64 v[30:31], v[4:5], 0, v[30:31]
	global_load_dword v27, v[30:31], off nt
.LBB0_1993:
	s_or_b64 exec, exec, s[8:9]
	v_mov_b32_e32 v29, 0
	v_mov_b32_e32 v30, 0
	s_and_saveexec_b64 s[8:9], vcc
	s_cbranch_execz .LBB0_1995
	v_or_b32_e32 v30, 36, v6
	v_ashrrev_i32_e32 v31, 31, v30
	v_lshlrev_b64 v[30:31], 12, v[30:31]
	v_lshl_add_u64 v[30:31], v[4:5], 0, v[30:31]
	global_load_dword v30, v[30:31], off nt
.LBB0_1995:
	s_or_b64 exec, exec, s[8:9]
	s_and_saveexec_b64 s[8:9], vcc
	s_cbranch_execz .LBB0_1997
	v_or_b32_e32 v32, 38, v6
	v_ashrrev_i32_e32 v33, 31, v32
	v_lshlrev_b64 v[32:33], 12, v[32:33]
	v_lshl_add_u64 v[32:33], v[4:5], 0, v[32:33]
	global_load_dword v29, v[32:33], off nt
.LBB0_1997:
	s_or_b64 exec, exec, s[8:9]
	v_mov_b32_e32 v31, 0
	v_mov_b32_e32 v32, 0
	s_and_saveexec_b64 s[8:9], vcc
	s_cbranch_execz .LBB0_1999
	v_or_b32_e32 v32, 40, v6
	v_ashrrev_i32_e32 v33, 31, v32
	v_lshlrev_b64 v[32:33], 12, v[32:33]
	v_lshl_add_u64 v[32:33], v[4:5], 0, v[32:33]
	global_load_dword v32, v[32:33], off nt
.LBB0_1999:
	s_or_b64 exec, exec, s[8:9]
	s_and_saveexec_b64 s[8:9], vcc
	s_cbranch_execz .LBB0_2001
	v_or_b32_e32 v34, 42, v6
	v_ashrrev_i32_e32 v35, 31, v34
	v_lshlrev_b64 v[34:35], 12, v[34:35]
	v_lshl_add_u64 v[34:35], v[4:5], 0, v[34:35]
	global_load_dword v31, v[34:35], off nt
.LBB0_2001:
	s_or_b64 exec, exec, s[8:9]
	v_mov_b32_e32 v33, 0
	v_mov_b32_e32 v34, 0
	s_and_saveexec_b64 s[8:9], vcc
	s_cbranch_execz .LBB0_2003
	v_or_b32_e32 v34, 44, v6
	v_ashrrev_i32_e32 v35, 31, v34
	v_lshlrev_b64 v[34:35], 12, v[34:35]
	v_lshl_add_u64 v[34:35], v[4:5], 0, v[34:35]
	global_load_dword v34, v[34:35], off nt
.LBB0_2003:
	s_or_b64 exec, exec, s[8:9]
	s_and_saveexec_b64 s[8:9], vcc
	s_cbranch_execz .LBB0_2005
	v_or_b32_e32 v36, 46, v6
	v_ashrrev_i32_e32 v37, 31, v36
	v_lshlrev_b64 v[36:37], 12, v[36:37]
	v_lshl_add_u64 v[36:37], v[4:5], 0, v[36:37]
	global_load_dword v33, v[36:37], off nt
.LBB0_2005:
	s_or_b64 exec, exec, s[8:9]
	v_mov_b32_e32 v35, 0
	v_mov_b32_e32 v36, 0
	s_and_saveexec_b64 s[8:9], vcc
	s_cbranch_execz .LBB0_2007
	v_or_b32_e32 v36, 48, v6
	v_ashrrev_i32_e32 v37, 31, v36
	v_lshlrev_b64 v[36:37], 12, v[36:37]
	v_lshl_add_u64 v[36:37], v[4:5], 0, v[36:37]
	global_load_dword v36, v[36:37], off nt
.LBB0_2007:
	s_or_b64 exec, exec, s[8:9]
	s_and_saveexec_b64 s[8:9], vcc
	s_cbranch_execz .LBB0_2009
	v_or_b32_e32 v38, 50, v6
	v_ashrrev_i32_e32 v39, 31, v38
	v_lshlrev_b64 v[38:39], 12, v[38:39]
	v_lshl_add_u64 v[38:39], v[4:5], 0, v[38:39]
	global_load_dword v35, v[38:39], off nt
.LBB0_2009:
	s_or_b64 exec, exec, s[8:9]
	v_mov_b32_e32 v37, 0
	v_mov_b32_e32 v38, 0
	s_and_saveexec_b64 s[8:9], vcc
	s_cbranch_execz .LBB0_2011
	v_or_b32_e32 v38, 52, v6
	v_ashrrev_i32_e32 v39, 31, v38
	v_lshlrev_b64 v[38:39], 12, v[38:39]
	v_lshl_add_u64 v[38:39], v[4:5], 0, v[38:39]
	global_load_dword v38, v[38:39], off nt
.LBB0_2011:
	s_or_b64 exec, exec, s[8:9]
	s_and_saveexec_b64 s[8:9], vcc
	s_cbranch_execz .LBB0_2013
	v_or_b32_e32 v40, 54, v6
	v_ashrrev_i32_e32 v41, 31, v40
	v_lshlrev_b64 v[40:41], 12, v[40:41]
	v_lshl_add_u64 v[40:41], v[4:5], 0, v[40:41]
	global_load_dword v37, v[40:41], off nt
.LBB0_2013:
	s_or_b64 exec, exec, s[8:9]
	v_mov_b32_e32 v39, 0
	v_mov_b32_e32 v40, 0
	s_and_saveexec_b64 s[8:9], vcc
	s_cbranch_execz .LBB0_2015
	v_or_b32_e32 v40, 56, v6
	v_ashrrev_i32_e32 v41, 31, v40
	v_lshlrev_b64 v[40:41], 12, v[40:41]
	v_lshl_add_u64 v[40:41], v[4:5], 0, v[40:41]
	global_load_dword v40, v[40:41], off nt
.LBB0_2015:
	s_or_b64 exec, exec, s[8:9]
	s_and_saveexec_b64 s[8:9], vcc
	s_cbranch_execz .LBB0_2017
	v_or_b32_e32 v42, 58, v6
	v_ashrrev_i32_e32 v43, 31, v42
	v_lshlrev_b64 v[42:43], 12, v[42:43]
	v_lshl_add_u64 v[42:43], v[4:5], 0, v[42:43]
	global_load_dword v39, v[42:43], off nt
.LBB0_2017:
	s_or_b64 exec, exec, s[8:9]
	v_mov_b32_e32 v41, 0
	v_mov_b32_e32 v42, 0
	s_and_saveexec_b64 s[8:9], vcc
	s_cbranch_execz .LBB0_2019
	v_or_b32_e32 v42, 60, v6
	v_ashrrev_i32_e32 v43, 31, v42
	v_lshlrev_b64 v[42:43], 12, v[42:43]
	v_lshl_add_u64 v[42:43], v[4:5], 0, v[42:43]
	global_load_dword v42, v[42:43], off nt
.LBB0_2019:
	s_or_b64 exec, exec, s[8:9]
	s_and_saveexec_b64 s[8:9], vcc
	s_cbranch_execz .LBB0_1956
	v_or_b32_e32 v44, 62, v6
	v_ashrrev_i32_e32 v45, 31, v44
	v_lshlrev_b64 v[44:45], 12, v[44:45]
	v_lshl_add_u64 v[4:5], v[4:5], 0, v[44:45]
	global_load_dword v41, v[4:5], off nt
	s_branch .LBB0_1956
